# v12 + second modulated rmsnorm (phase G) row loops software-prefetch the next row's streamed bf16 loads one iteration ahead; bit-identical
# speedup vs baseline: 1.0054x; 1.0010x over previous
; __device__ __forceinline__ float bf_lo(unsigned w) { return __uint_as_float(w << 16); }
; __device__ __forceinline__ float bf_hi(unsigned w) { return __uint_as_float(w & 0xffff0000u); }
; template <bool MOD, bool SRC16>
; __device__ __forceinline__ void norm_rows(const float* src, int nrows, int tok0, const float* g, const float* ada, int sh_off, int sc_off, bf16* dst, float* dstf, int gw, int NGW, int lane_in) {
;     ...
;     for (int m = gw; m < nrows; m += NGW) {
;         f32x4 v[8]; float s = 0.f;
;         if (SRC16) { const v4u* xh = (const v4u*)((const bf16*)src + (size_t)m * 4096) + lane;
; #pragma unroll
;             for (int j = 0; j < 4; ++j) { const v4u w = xh[64 * j]; v[2 * j] = (f32x4){pg8::bf_lo(w.x), pg8::bf_hi(w.x), pg8::bf_lo(w.y), pg8::bf_hi(w.y)}; v[2 * j + 1] = (f32x4){pg8::bf_lo(w.z), pg8::bf_hi(w.z), pg8::bf_lo(w.w), pg8::bf_hi(w.w)}; } }
;         else { const f32x4* xr = (const f32x4*)(src + (size_t)m * DM) + lane;
; #pragma unroll
;             for (int j = 0; j < 8; ++j) v[j] = __builtin_nontemporal_load(xr + 64 * j); }
; #pragma unroll
;         for (int j = 0; j < 8; ++j) { s += (v[j].x * v[j].x + v[j].y * v[j].y) + (v[j].z * v[j].z + v[j].w * v[j].w); }
;         const float r = 1.0f / sqrtf(wave_sum(s) * (1.f / DM) + EPS);
;         if (MOD) {
;             const int b = batch_of(tok0 + m); const float* ab = ada + (size_t)b * ADAW;
;             f32x4 y[8];
; #pragma unroll
;             for (int j = 0; j < 8; ++j) { const int col = SRC16 ? 8 * (lane + 64 * (j >> 1)) + 4 * (j & 1) : 4 * (lane + 64 * j);
;                 const f32x4 gv = *(const f32x4*)(g + col), sc = *(const f32x4*)(ab + sc_off + col), sh = *(const f32x4*)(ab + sh_off + col);
;                 y[j] = (v[j] * r) * gv * (sc + 1.0f) + sh; }
.LBB0_632:
	s_or_b64 exec, exec, s[0:1]
	v_readlane_b32 s0, v248, 1
	s_mov_b32 s2, s91
	v_readlane_b32 s1, v248, 2
	s_mov_b32 s3, s64
	s_waitcnt lgkmcnt(0)
	s_barrier
	v_mov_b32_e32 v0, v192
	v_readlane_b32 s2, v248, 41
	v_readlane_b32 s3, v248, 42
	s_and_b64 vcc, exec, s[2:3]
	s_cbranch_vccz .LBB0_635
	v_readlane_b32 s4, v248, 7
	v_readlane_b32 s5, v248, 8
	s_add_u32 s2, s0, 0x100000
	v_readlane_b32 s4, v248, 39
	s_addc_u32 s3, s1, 0
	v_readlane_b32 s5, v248, 40
	s_mov_b32 s16, s4
	s_ashr_i32 s17, s4, 31
	v_lshlrev_b32_e32 v2, 3, v0
	s_lshl_b64 s[4:5], s[16:17], 12
	v_readlane_b32 s8, v248, 11
	v_readlane_b32 s9, v248, 12
	v_readlane_b32 s10, v248, 13
	v_readlane_b32 s11, v248, 14
	v_add_u32_e32 v6, 0x200, v2
	v_add_u32_e32 v10, 0x400, v2
	v_add_u32_e32 v14, 0x600, v2
	s_add_u32 s4, s0, s4
	v_ashrrev_i32_e32 v3, 31, v2
	v_readlane_b32 s6, v248, 9
	v_readlane_b32 s7, v248, 10
	v_ashrrev_i32_e32 v7, 31, v6
	v_ashrrev_i32_e32 v11, 31, v10
	v_ashrrev_i32_e32 v15, 31, v14
	s_addc_u32 s5, s1, s5
	s_ashr_i32 s69, s68, 31
	v_readlane_b32 s8, v248, 3
	v_lshl_add_u64 v[32:33], v[2:3], 2, s[6:7]
	v_or_b32_e32 v4, 4, v2
	v_add_u32_e32 v8, 0x204, v2
	v_lshl_add_u64 v[34:35], v[6:7], 2, s[6:7]
	v_lshl_add_u64 v[36:37], v[10:11], 2, s[6:7]
	v_add_u32_e32 v12, 0x404, v2
	v_lshl_add_u64 v[38:39], v[14:15], 2, s[6:7]
	v_add_u32_e32 v16, 0x604, v2
	s_lshl_b64 s[6:7], s[68:69], 12
	s_lshl_b64 s[0:1], s[16:17], 13
	v_readlane_b32 s10, v248, 5
	v_ashrrev_i32_e32 v1, 31, v0
	v_ashrrev_i32_e32 v5, 31, v4
	v_ashrrev_i32_e32 v9, 31, v8
	v_ashrrev_i32_e32 v13, 31, v12
	v_ashrrev_i32_e32 v17, 31, v16
	v_readlane_b32 s9, v248, 4
	v_readlane_b32 s11, v248, 6
	s_add_u32 s8, s10, s0
	s_mov_b32 s0, s16
	v_lshlrev_b64 v[40:41], 4, v[0:1]
	s_addc_u32 s9, s11, s1
	s_lshl_b64 s[12:13], s[68:69], 13
	s_mov_b32 s10, 0xffff0000
	v_mov_b32_e32 v60, 0x358637bd
	s_mov_b32 s11, 0xf800000
	v_mov_b32_e32 v61, 0x260
	v_lshlrev_b64 v[42:43], 2, v[2:3]
	v_lshlrev_b64 v[44:45], 2, v[4:5]
	v_lshlrev_b64 v[46:47], 2, v[6:7]
	v_lshlrev_b64 v[48:49], 2, v[8:9]
	v_lshlrev_b64 v[50:51], 2, v[10:11]
	v_lshlrev_b64 v[52:53], 2, v[12:13]
	v_lshlrev_b64 v[54:55], 2, v[14:15]
	v_lshlrev_b64 v[56:57], 2, v[16:17]
	s_movk_i32 s14, 0x7fff
	s_mov_b32 s15, 0x7a00000
	v_writelane_b32 v248, s0, 39
	s_nop 1
	v_writelane_b32 v248, s1, 40
	v_lshl_add_u64 v[226:227], s[8:9], 0, v[40:41]
	global_load_dwordx4 v[210:213], v[226:227], off offset:1024
	global_load_dwordx4 v[214:217], v[226:227], off offset:2048
	global_load_dwordx4 v[218:221], v[226:227], off offset:3072
	global_load_dwordx4 v[222:225], v[226:227], off
.LBB0_634:
	global_load_dwordx4 v[0:3], v[32:33], off offset:16
	global_load_dwordx4 v[4:7], v[32:33], off
	global_load_dwordx4 v[8:11], v[32:33], off offset:2048
	global_load_dwordx4 v[12:15], v[34:35], off offset:16
	global_load_dwordx4 v[16:19], v[36:37], off offset:16
	global_load_dwordx4 v[20:23], v[36:37], off
	global_load_dwordx4 v[24:27], v[38:39], off offset:16
	global_load_dwordx4 v[28:31], v[38:39], off
	s_ashr_i32 s0, s16, 12
	s_mul_hi_i32 s1, s0, 0xc000
	s_mul_i32 s0, s0, 0xc000
	s_add_u32 s0, s2, s0
	s_addc_u32 s1, s3, s1
	v_lshl_add_u64 v[78:79], s[4:5], 0, v[40:41]
	s_add_u32 s18, s0, 0x8000
	v_add_co_u32_e32 v58, vcc, s15, v78
	s_addc_u32 s19, s1, 0
	s_nop 0
	v_addc_co_u32_e32 v59, vcc, 0, v79, vcc
	v_lshl_add_u64 v[78:79], s[18:19], 0, v[42:43]
	v_lshl_add_u64 v[82:83], s[18:19], 0, v[44:45]
	v_lshl_add_u64 v[86:87], s[18:19], 0, v[46:47]
	v_lshl_add_u64 v[90:91], s[18:19], 0, v[48:49]
	v_lshl_add_u64 v[94:95], s[18:19], 0, v[50:51]
	v_lshl_add_u64 v[98:99], s[18:19], 0, v[52:53]
	v_lshl_add_u64 v[102:103], s[18:19], 0, v[54:55]
	v_lshl_add_u64 v[106:107], s[18:19], 0, v[56:57]
	flat_load_dwordx4 v[78:81], v[78:79]
	s_nop 0
	flat_load_dwordx4 v[82:85], v[82:83]
	s_nop 0
	flat_load_dwordx4 v[86:89], v[86:87]
	s_nop 0
	flat_load_dwordx4 v[90:93], v[90:91]
	s_nop 0
	flat_load_dwordx4 v[94:97], v[94:95]
	s_nop 0
	flat_load_dwordx4 v[98:101], v[98:99]
	s_nop 0
	flat_load_dwordx4 v[102:105], v[102:103]
	s_nop 0
	flat_load_dwordx4 v[106:109], v[106:107]
	s_add_u32 s0, s0, 0x6000
	s_addc_u32 s1, s1, 0
	v_lshl_add_u64 v[110:111], s[0:1], 0, v[42:43]
	v_lshl_add_u64 v[114:115], s[0:1], 0, v[44:45]
	v_lshl_add_u64 v[118:119], s[0:1], 0, v[46:47]
	v_lshl_add_u64 v[122:123], s[0:1], 0, v[48:49]
	v_lshl_add_u64 v[126:127], s[0:1], 0, v[50:51]
	v_lshl_add_u64 v[130:131], s[0:1], 0, v[52:53]
	v_lshl_add_u64 v[134:135], s[0:1], 0, v[54:55]
	v_lshl_add_u64 v[138:139], s[0:1], 0, v[56:57]
	flat_load_dwordx4 v[110:113], v[110:111]
	s_nop 0
	flat_load_dwordx4 v[114:117], v[114:115]
	s_nop 0
	flat_load_dwordx4 v[118:121], v[118:119]
	s_nop 0
	flat_load_dwordx4 v[122:125], v[122:123]
	s_nop 0
	flat_load_dwordx4 v[126:129], v[126:127]
	s_nop 0
	flat_load_dwordx4 v[130:133], v[130:131]
	s_nop 0
	flat_load_dwordx4 v[134:137], v[134:135]
	s_nop 0
	flat_load_dwordx4 v[138:141], v[138:139]
	s_add_i32 s16, s16, s68
	s_add_u32 s4, s4, s6
	s_addc_u32 s5, s5, s7
	s_add_u32 s8, s8, s12
	s_addc_u32 s9, s9, s13
	s_cmpk_lt_i32 s16, 0x4000
	s_waitcnt vmcnt(0)
	v_mov_b64_e32 v[62:63], v[210:211]
	v_mov_b64_e32 v[64:65], v[212:213]
	v_mov_b64_e32 v[66:67], v[214:215]
	v_mov_b64_e32 v[68:69], v[216:217]
	v_mov_b64_e32 v[70:71], v[218:219]
	v_mov_b64_e32 v[72:73], v[220:221]
	v_mov_b64_e32 v[74:75], v[222:223]
	v_mov_b64_e32 v[76:77], v[224:225]
	s_cmpk_lt_i32 s16, 0x4000
	s_cbranch_scc0 .Lg_nopf_0
	v_lshl_add_u64 v[226:227], s[8:9], 0, v[40:41]
	global_load_dwordx4 v[210:213], v[226:227], off offset:1024
	global_load_dwordx4 v[214:217], v[226:227], off offset:2048
	global_load_dwordx4 v[218:221], v[226:227], off offset:3072
	global_load_dwordx4 v[222:225], v[226:227], off
; __device__ __forceinline__ float bf_lo(unsigned w) { return __uint_as_float(w << 16); }
; __device__ __forceinline__ float bf_hi(unsigned w) { return __uint_as_float(w & 0xffff0000u); }
; __device__ __forceinline__ float wave_sum(float v) {
; #pragma unroll
;     for (int o = 1; o < 64; o <<= 1) v += __shfl_xor(v, o);
;     return v;
; }
; template <bool MOD, bool SRC16>
; __device__ __forceinline__ void norm_rows(const float* src, int nrows, int tok0, const float* g, const float* ada, int sh_off, int sc_off, bf16* dst, float* dstf, int gw, int NGW, int lane_in) {
;     ...
;         if (SRC16) { const v4u* xh = (const v4u*)((const bf16*)src + (size_t)m * 4096) + lane;
; #pragma unroll
;             for (int j = 0; j < 4; ++j) { const v4u w = xh[64 * j]; v[2 * j] = (f32x4){pg8::bf_lo(w.x), pg8::bf_hi(w.x), pg8::bf_lo(w.y), pg8::bf_hi(w.y)}; v[2 * j + 1] = (f32x4){pg8::bf_lo(w.z), pg8::bf_hi(w.z), pg8::bf_lo(w.w), pg8::bf_hi(w.w)}; } }
;         else { const f32x4* xr = (const f32x4*)(src + (size_t)m * DM) + lane;
; #pragma unroll
;             for (int j = 0; j < 8; ++j) v[j] = __builtin_nontemporal_load(xr + 64 * j); }
; #pragma unroll
;         for (int j = 0; j < 8; ++j) { s += (v[j].x * v[j].x + v[j].y * v[j].y) + (v[j].z * v[j].z + v[j].w * v[j].w); }
;         const float r = 1.0f / sqrtf(wave_sum(s) * (1.f / DM) + EPS);
.Lg_nopf_0:
	v_lshlrev_b32_e32 v142, 16, v64
	v_and_b32_e32 v143, 0xffff0000, v64
	v_lshlrev_b32_e32 v64, 16, v66
	v_lshlrev_b32_e32 v147, 16, v76
	v_and_b32_e32 v149, 0xffff0000, v76
	v_and_b32_e32 v148, 0xffff0000, v74
	v_lshlrev_b32_e32 v151, 16, v77
	v_and_b32_e32 v77, 0xffff0000, v77
	v_and_b32_e32 v76, 0xffff0000, v75
	v_lshlrev_b32_e32 v146, 16, v74
	v_lshlrev_b32_e32 v150, 16, v75
	v_lshlrev_b32_e32 v75, 16, v63
	v_lshlrev_b32_e32 v74, 16, v62
	v_and_b32_e32 v63, 0xffff0000, v63
	v_and_b32_e32 v62, 0xffff0000, v62
	v_pk_mul_f32 v[158:159], v[148:149], v[148:149]
	v_pk_mul_f32 v[160:161], v[76:77], v[76:77]
	v_lshlrev_b32_e32 v152, 16, v65
	v_lshlrev_b32_e32 v155, 16, v69
	v_lshlrev_b32_e32 v154, 16, v68
	v_and_b32_e32 v69, 0xffff0000, v69
	v_and_b32_e32 v68, 0xffff0000, v68
	v_pk_mul_f32 v[162:163], v[62:63], v[62:63]
	v_mov_b32_e32 v178, v150
	v_mov_b32_e32 v179, v76
	v_mov_b32_e32 v180, v146
	v_mov_b32_e32 v181, v148
	v_mov_b32_e32 v76, v151
	v_mov_b32_e32 v148, v147
	v_pk_fma_f32 v[146:147], v[146:147], v[146:147], v[158:159]
	v_pk_fma_f32 v[150:151], v[150:151], v[150:151], v[160:161]
	v_and_b32_e32 v153, 0xffff0000, v65
	v_mul_f32_e32 v65, v142, v142
	v_mul_f32_e32 v165, v143, v143
	v_mul_f32_e32 v166, v152, v152
	v_mov_b32_e32 v164, v64
	v_pk_mul_f32 v[170:171], v[68:69], v[68:69]
	v_mov_b32_e32 v182, v75
	v_mov_b32_e32 v183, v63
	v_pk_fma_f32 v[158:159], v[74:75], v[74:75], v[162:163]
	v_mov_b32_e32 v75, v62
	v_pk_add_f32 v[62:63], v[146:147], v[150:151]
	v_and_b32_e32 v169, 0xffff0000, v66
	v_lshlrev_b32_e32 v66, 16, v67
	v_and_b32_e32 v67, 0xffff0000, v67
	v_mov_b32_e32 v184, v155
	v_mov_b32_e32 v185, v69
	v_pk_fma_f32 v[160:161], v[152:153], v[152:153], v[166:167] op_sel_hi:[1,1,0]
	v_pk_add_f32 v[162:163], v[64:65], v[164:165]
	v_pk_fma_f32 v[164:165], v[154:155], v[154:155], v[170:171]
	v_mov_b32_e32 v155, v68
	v_pk_add_f32 v[68:69], v[158:159], v[158:159] op_sel_hi:[0,1]
	v_pk_add_f32 v[62:63], v[62:63], v[62:63] op_sel_hi:[0,1]
	v_mul_f32_e32 v168, v64, v64
	v_mov_b32_e32 v65, v169
	v_mul_f32_e32 v160, v169, v169
	v_mov_b32_e32 v169, v163
	v_mul_f32_e32 v68, v67, v67
	v_mul_f32_e32 v62, v66, v66
	v_lshlrev_b32_e32 v144, 16, v70
	v_and_b32_e32 v145, 0xffff0000, v70
	v_lshlrev_b32_e32 v70, 16, v72
	v_lshlrev_b32_e32 v156, 16, v71
	v_pk_add_f32 v[150:151], v[168:169], v[160:161]
	v_pk_add_f32 v[62:63], v[62:63], v[68:69]
	v_and_b32_e32 v175, 0xffff0000, v72
	v_and_b32_e32 v157, 0xffff0000, v71
	v_mul_f32_e32 v71, v144, v144
	v_mul_f32_e32 v173, v145, v145
	v_mul_f32_e32 v174, v156, v156
	v_mov_b32_e32 v172, v70
	v_pk_add_f32 v[62:63], v[150:151], v[62:63]
	v_lshlrev_b32_e32 v72, 16, v73
	v_and_b32_e32 v73, 0xffff0000, v73
	v_pk_fma_f32 v[166:167], v[156:157], v[156:157], v[174:175] op_sel_hi:[1,1,0]
	v_pk_add_f32 v[170:171], v[70:71], v[172:173]
	v_pk_add_f32 v[146:147], v[164:165], v[164:165] op_sel_hi:[0,1]
	v_pk_add_f32 v[62:63], v[62:63], v[62:63] op_sel_hi:[0,1]
	v_mul_f32_e32 v176, v70, v70
	v_mul_f32_e32 v166, v175, v175
	v_mov_b32_e32 v177, v171
	v_mul_f32_e32 v146, v72, v72
	v_mul_f32_e32 v62, v73, v73
	v_pk_add_f32 v[158:159], v[176:177], v[166:167]
	v_pk_add_f32 v[62:63], v[146:147], v[62:63]
	s_waitcnt lgkmcnt(0)
	v_pk_add_f32 v[68:69], v[80:81], 1.0 op_sel_hi:[1,0]
	v_pk_add_f32 v[62:63], v[158:159], v[62:63]
	v_pk_add_f32 v[80:81], v[84:85], 1.0 op_sel_hi:[1,0]
	v_add_f32_e32 v62, v62, v63
	ds_bpermute_b32 v63, v195, v62
	v_pk_add_f32 v[84:85], v[88:89], 1.0 op_sel_hi:[1,0]
	v_pk_add_f32 v[88:89], v[92:93], 1.0 op_sel_hi:[1,0]
	v_pk_add_f32 v[92:93], v[96:97], 1.0 op_sel_hi:[1,0]
	v_pk_add_f32 v[96:97], v[100:101], 1.0 op_sel_hi:[1,0]
	s_waitcnt lgkmcnt(0)
	v_add_f32_e32 v62, v62, v63
	ds_bpermute_b32 v63, v202, v62
	v_pk_add_f32 v[100:101], v[104:105], 1.0 op_sel_hi:[1,0]
	v_pk_add_f32 v[104:105], v[108:109], 1.0 op_sel_hi:[1,0]
	v_mov_b32_e32 v71, v175
	v_pk_add_f32 v[78:79], v[78:79], 1.0 op_sel_hi:[1,0]
	s_waitcnt lgkmcnt(0)
	v_add_f32_e32 v62, v62, v63
	ds_bpermute_b32 v63, v203, v62
	v_pk_add_f32 v[82:83], v[82:83], 1.0 op_sel_hi:[1,0]
	v_pk_add_f32 v[86:87], v[86:87], 1.0 op_sel_hi:[1,0]
	v_pk_add_f32 v[90:91], v[90:91], 1.0 op_sel_hi:[1,0]
	v_pk_add_f32 v[94:95], v[94:95], 1.0 op_sel_hi:[1,0]
	s_waitcnt lgkmcnt(0)
	v_add_f32_e32 v62, v62, v63
	ds_bpermute_b32 v63, v204, v62
	v_pk_add_f32 v[98:99], v[98:99], 1.0 op_sel_hi:[1,0]
	v_pk_add_f32 v[102:103], v[102:103], 1.0 op_sel_hi:[1,0]
	v_pk_add_f32 v[106:107], v[106:107], 1.0 op_sel_hi:[1,0]
	s_waitcnt lgkmcnt(0)
	v_add_f32_e32 v62, v62, v63
	ds_bpermute_b32 v63, v205, v62
	s_waitcnt lgkmcnt(0)
	v_add_f32_e32 v62, v62, v63
	ds_bpermute_b32 v63, v206, v62
	s_waitcnt lgkmcnt(0)
; __device__ __forceinline__ unsigned pk2(float lo, float hi) { return f2bf(lo) | (f2bf(hi) << 16); }
; template <bool MOD, bool SRC16>
; __device__ __forceinline__ void norm_rows(const float* src, int nrows, int tok0, const float* g, const float* ada, int sh_off, int sc_off, bf16* dst, float* dstf, int gw, int NGW, int lane_in) {
;     ...
;         const float r = 1.0f / sqrtf(wave_sum(s) * (1.f / DM) + EPS);
;         if (MOD) {
;             const int b = batch_of(tok0 + m); const float* ab = ada + (size_t)b * ADAW;
;             f32x4 y[8];
; #pragma unroll
;             for (int j = 0; j < 8; ++j) { const int col = SRC16 ? 8 * (lane + 64 * (j >> 1)) + 4 * (j & 1) : 4 * (lane + 64 * j);
;                 const f32x4 gv = *(const f32x4*)(g + col), sc = *(const f32x4*)(ab + sc_off + col), sh = *(const f32x4*)(ab + sh_off + col);
;                 y[j] = (v[j] * r) * gv * (sc + 1.0f) + sh; }
;             if (SRC16) { v4u* o16 = (v4u*)(dst + (size_t)m * DM) + lane;
; #pragma unroll
;                 for (int j = 0; j < 4; ++j) { v4u w; w.x = pk2(y[2 * j].x, y[2 * j].y); w.y = pk2(y[2 * j].z, y[2 * j].w); w.z = pk2(y[2 * j + 1].x, y[2 * j + 1].y); w.w = pk2(y[2 * j + 1].z, y[2 * j + 1].w); o16[64 * j] = w; } }
	v_add_f32_e32 v62, v62, v63
	v_fmamk_f32 v62, v62, 0x3a000000, v60
	v_mul_f32_e32 v63, 0x4f800000, v62
	v_cmp_gt_f32_e32 vcc, s11, v62
	s_nop 1
	v_cndmask_b32_e32 v62, v62, v63, vcc
	v_sqrt_f32_e32 v63, v62
	s_nop 0
	v_add_u32_e32 v108, -1, v63
	v_add_u32_e32 v109, 1, v63
	v_fma_f32 v146, -v108, v63, v62
	v_fma_f32 v147, -v109, v63, v62
	v_cmp_ge_f32_e64 s[0:1], 0, v146
	s_nop 1
	v_cndmask_b32_e64 v63, v63, v108, s[0:1]
	v_cmp_lt_f32_e64 s[0:1], 0, v147
	s_nop 1
	v_cndmask_b32_e64 v63, v63, v109, s[0:1]
	v_mul_f32_e32 v108, 0x37800000, v63
	v_cndmask_b32_e32 v63, v63, v108, vcc
	v_cmp_class_f32_e32 vcc, v62, v61
	s_nop 1
	v_cndmask_b32_e32 v62, v63, v62, vcc
	v_div_scale_f32 v63, s[0:1], v62, v62, 1.0
	v_rcp_f32_e32 v109, v63
	v_div_scale_f32 v108, vcc, 1.0, v62, 1.0
	v_fma_f32 v146, -v63, v109, 1.0
	v_fmac_f32_e32 v109, v146, v109
	v_mul_f32_e32 v146, v108, v109
	v_fma_f32 v147, -v63, v146, v108
	v_fmac_f32_e32 v146, v147, v109
	v_fma_f32 v63, -v63, v146, v108
	v_div_fmas_f32 v63, v63, v109, v146
	v_div_fixup_f32 v62, v63, v62, 1.0
	v_pk_mul_f32 v[108:109], v[178:179], v[62:63] op_sel_hi:[1,0]
	v_pk_mul_f32 v[146:147], v[180:181], v[62:63] op_sel_hi:[1,0]
	v_pk_mul_f32 v[76:77], v[76:77], v[62:63] op_sel_hi:[1,0]
	v_pk_mul_f32 v[148:149], v[148:149], v[62:63] op_sel_hi:[1,0]
	v_pk_mul_f32 v[150:151], v[62:63], v[182:183] op_sel_hi:[0,1]
	v_pk_mul_f32 v[74:75], v[62:63], v[74:75] op_sel_hi:[0,1]
	v_pk_mul_f32 v[152:153], v[152:153], v[62:63] op_sel_hi:[1,0]
	v_pk_mul_f32 v[142:143], v[142:143], v[62:63] op_sel_hi:[1,0]
	v_pk_mul_f32 v[66:67], v[66:67], v[62:63] op_sel_hi:[1,0]
	v_pk_mul_f32 v[64:65], v[64:65], v[62:63] op_sel_hi:[1,0]
	v_pk_mul_f32 v[158:159], v[62:63], v[184:185] op_sel_hi:[0,1]
	v_pk_mul_f32 v[154:155], v[62:63], v[154:155] op_sel_hi:[0,1]
	v_pk_mul_f32 v[156:157], v[156:157], v[62:63] op_sel_hi:[1,0]
	v_pk_mul_f32 v[144:145], v[144:145], v[62:63] op_sel_hi:[1,0]
	v_pk_mul_f32 v[72:73], v[72:73], v[62:63] op_sel_hi:[1,0]
	v_pk_mul_f32 v[62:63], v[70:71], v[62:63] op_sel_hi:[1,0]
	v_pk_mul_f32 v[4:5], v[4:5], v[146:147]
	v_pk_mul_f32 v[6:7], v[6:7], v[108:109]
	v_pk_mul_f32 v[0:1], v[0:1], v[148:149]
	v_pk_mul_f32 v[2:3], v[2:3], v[76:77]
	v_pk_mul_f32 v[8:9], v[8:9], v[74:75]
	v_pk_mul_f32 v[10:11], v[10:11], v[150:151]
	v_pk_mul_f32 v[12:13], v[12:13], v[142:143]
	v_pk_mul_f32 v[14:15], v[14:15], v[152:153]
	v_pk_mul_f32 v[20:21], v[20:21], v[64:65]
	v_pk_mul_f32 v[22:23], v[22:23], v[66:67]
	v_pk_mul_f32 v[16:17], v[16:17], v[154:155]
	v_pk_mul_f32 v[18:19], v[18:19], v[158:159]
	v_pk_mul_f32 v[28:29], v[144:145], v[28:29]
	v_pk_mul_f32 v[30:31], v[156:157], v[30:31]
	v_pk_mul_f32 v[24:25], v[62:63], v[24:25]
	v_pk_mul_f32 v[26:27], v[72:73], v[26:27]
	v_pk_fma_f32 v[6:7], v[68:69], v[6:7], v[112:113]
	v_pk_fma_f32 v[4:5], v[78:79], v[4:5], v[110:111]
	v_pk_fma_f32 v[2:3], v[80:81], v[2:3], v[116:117]
	v_pk_fma_f32 v[0:1], v[82:83], v[0:1], v[114:115]
	v_pk_fma_f32 v[10:11], v[84:85], v[10:11], v[120:121]
	v_pk_fma_f32 v[8:9], v[86:87], v[8:9], v[118:119]
	v_pk_fma_f32 v[14:15], v[88:89], v[14:15], v[124:125]
	v_pk_fma_f32 v[12:13], v[90:91], v[12:13], v[122:123]
	v_pk_fma_f32 v[22:23], v[92:93], v[22:23], v[128:129]
	v_pk_fma_f32 v[20:21], v[94:95], v[20:21], v[126:127]
	v_pk_fma_f32 v[18:19], v[18:19], v[96:97], v[132:133]
	v_pk_fma_f32 v[16:17], v[16:17], v[98:99], v[130:131]
	v_pk_fma_f32 v[30:31], v[30:31], v[100:101], v[136:137]
	v_pk_fma_f32 v[28:29], v[28:29], v[102:103], v[134:135]
	v_pk_fma_f32 v[26:27], v[26:27], v[104:105], v[140:141]
	v_pk_fma_f32 v[24:25], v[24:25], v[106:107], v[138:139]
	v_bfe_u32 v62, v4, 16, 1
	v_bfe_u32 v64, v6, 16, 1
	v_bfe_u32 v66, v0, 16, 1
	v_bfe_u32 v67, v1, 16, 1
	v_bfe_u32 v68, v2, 16, 1
	v_bfe_u32 v63, v5, 16, 1
	v_bfe_u32 v65, v7, 16, 1
	v_bfe_u32 v69, v3, 16, 1
	v_bfe_u32 v70, v8, 16, 1
	v_bfe_u32 v71, v9, 16, 1
	v_bfe_u32 v72, v10, 16, 1
	v_bfe_u32 v73, v11, 16, 1
	v_bfe_u32 v74, v12, 16, 1
	v_bfe_u32 v75, v13, 16, 1
	v_bfe_u32 v76, v14, 16, 1
	v_bfe_u32 v77, v15, 16, 1
	v_bfe_u32 v78, v20, 16, 1
	v_bfe_u32 v79, v21, 16, 1
	v_bfe_u32 v80, v22, 16, 1
	v_bfe_u32 v81, v23, 16, 1
	v_bfe_u32 v82, v16, 16, 1
	v_bfe_u32 v84, v18, 16, 1
	v_bfe_u32 v86, v28, 16, 1
	v_bfe_u32 v87, v29, 16, 1
	v_bfe_u32 v88, v30, 16, 1
	v_bfe_u32 v89, v31, 16, 1
	v_bfe_u32 v90, v24, 16, 1
	v_bfe_u32 v92, v26, 16, 1
	v_add3_u32 v4, v4, v62, s14
	v_add3_u32 v6, v6, v64, s14
	v_add3_u32 v0, v0, v66, s14
	v_add3_u32 v62, v1, v67, s14
	v_add3_u32 v1, v2, v68, s14
	v_bfe_u32 v83, v17, 16, 1
	v_bfe_u32 v85, v19, 16, 1
	v_bfe_u32 v91, v25, 16, 1
	v_bfe_u32 v93, v27, 16, 1
	v_add3_u32 v5, v5, v63, s14
	v_add3_u32 v7, v7, v65, s14
	v_add3_u32 v3, v3, v69, s14
	v_add3_u32 v2, v8, v70, s14
	v_add3_u32 v8, v9, v71, s14
	v_add3_u32 v9, v10, v72, s14
	v_add3_u32 v10, v11, v73, s14
	v_add3_u32 v11, v12, v74, s14
	v_add3_u32 v12, v13, v75, s14
	v_add3_u32 v13, v14, v76, s14
	v_add3_u32 v14, v15, v77, s14
	v_add3_u32 v15, v20, v78, s14
	v_add3_u32 v20, v21, v79, s14
	v_add3_u32 v21, v22, v80, s14
	v_add3_u32 v22, v23, v81, s14
	v_add3_u32 v16, v16, v82, s14
	v_add3_u32 v18, v18, v84, s14
	v_add3_u32 v23, v28, v86, s14
	v_add3_u32 v28, v29, v87, s14
	v_add3_u32 v29, v30, v88, s14
	v_add3_u32 v30, v31, v89, s14
	v_add3_u32 v24, v24, v90, s14
	v_add3_u32 v26, v26, v92, s14
	v_lshrrev_b32_e32 v4, 16, v4
	v_lshrrev_b32_e32 v6, 16, v6
	v_lshrrev_b32_e32 v31, 16, v0
	v_lshrrev_b32_e32 v63, 16, v1
	v_add3_u32 v17, v17, v83, s14
	v_add3_u32 v19, v19, v85, s14
	v_add3_u32 v25, v25, v91, s14
	v_add3_u32 v27, v27, v93, s14
	v_lshrrev_b32_e32 v64, 16, v2
	v_lshrrev_b32_e32 v9, 16, v9
	v_lshrrev_b32_e32 v11, 16, v11
	v_lshrrev_b32_e32 v13, 16, v13
	v_lshrrev_b32_e32 v15, 16, v15
	v_lshrrev_b32_e32 v21, 16, v21
	v_lshrrev_b32_e32 v16, 16, v16
	v_lshrrev_b32_e32 v18, 16, v18
	v_lshrrev_b32_e32 v23, 16, v23
	v_lshrrev_b32_e32 v29, 16, v29
	v_lshrrev_b32_e32 v24, 16, v24
	v_lshrrev_b32_e32 v26, 16, v26
	v_and_or_b32 v0, v5, s10, v4
	v_and_or_b32 v1, v7, s10, v6
	v_and_or_b32 v2, v62, s10, v31
	v_and_or_b32 v3, v3, s10, v63
	v_and_or_b32 v4, v8, s10, v64
	v_and_or_b32 v5, v10, s10, v9
	v_and_or_b32 v6, v12, s10, v11
	v_and_or_b32 v7, v14, s10, v13
	v_and_or_b32 v8, v20, s10, v15
	v_and_or_b32 v9, v22, s10, v21
	v_and_or_b32 v10, v17, s10, v16
	v_and_or_b32 v11, v19, s10, v18
	v_and_or_b32 v12, v28, s10, v23
	v_and_or_b32 v13, v30, s10, v29
	v_and_or_b32 v14, v25, s10, v24
	v_and_or_b32 v15, v27, s10, v26
	flat_store_dwordx4 v[58:59], v[0:3]
	flat_store_dwordx4 v[58:59], v[4:7] offset:1024
	flat_store_dwordx4 v[58:59], v[8:11] offset:2048
	flat_store_dwordx4 v[58:59], v[12:15] offset:3072
	s_cmpk_lt_i32 s16, 0x4000
	s_cbranch_scc1 .LBB0_634

; __device__ __forceinline__ float bf_lo(unsigned w) { return __uint_as_float(w << 16); }
; __device__ __forceinline__ float bf_hi(unsigned w) { return __uint_as_float(w & 0xffff0000u); }
; template <bool MOD, bool SRC16>
; __device__ __forceinline__ void norm_rows(const float* src, int nrows, int tok0, const float* g, const float* ada, int sh_off, int sc_off, bf16* dst, float* dstf, int gw, int NGW, int lane_in) {
;     ...
;     for (int m = gw; m < nrows; m += NGW) {
;         f32x4 v[8]; float s = 0.f;
;         if (SRC16) { const v4u* xh = (const v4u*)((const bf16*)src + (size_t)m * 4096) + lane;
; #pragma unroll
;             for (int j = 0; j < 4; ++j) { const v4u w = xh[64 * j]; v[2 * j] = (f32x4){pg8::bf_lo(w.x), pg8::bf_hi(w.x), pg8::bf_lo(w.y), pg8::bf_hi(w.y)}; v[2 * j + 1] = (f32x4){pg8::bf_lo(w.z), pg8::bf_hi(w.z), pg8::bf_lo(w.w), pg8::bf_hi(w.w)}; } }
;         else { const f32x4* xr = (const f32x4*)(src + (size_t)m * DM) + lane;
; #pragma unroll
;             for (int j = 0; j < 8; ++j) v[j] = __builtin_nontemporal_load(xr + 64 * j); }
; #pragma unroll
;         for (int j = 0; j < 8; ++j) { s += (v[j].x * v[j].x + v[j].y * v[j].y) + (v[j].z * v[j].z + v[j].w * v[j].w); }
;         const float r = 1.0f / sqrtf(wave_sum(s) * (1.f / DM) + EPS);
;         if (MOD) {
;             const int b = batch_of(tok0 + m); const float* ab = ada + (size_t)b * ADAW;
;             f32x4 y[8];
; #pragma unroll
;             for (int j = 0; j < 8; ++j) { const int col = SRC16 ? 8 * (lane + 64 * (j >> 1)) + 4 * (j & 1) : 4 * (lane + 64 * j);
;                 const f32x4 gv = *(const f32x4*)(g + col), sc = *(const f32x4*)(ab + sc_off + col), sh = *(const f32x4*)(ab + sh_off + col);
;                 y[j] = (v[j] * r) * gv * (sc + 1.0f) + sh; }
.LBB0_1288:
	s_or_b64 exec, exec, s[0:1]
	v_readlane_b32 s0, v248, 1
	v_readlane_b32 s1, v248, 2
	s_mov_b32 s2, s67
	s_mov_b32 s3, s91
	s_waitcnt lgkmcnt(0)
	s_barrier
	v_mov_b32_e32 v0, v192
	v_readlane_b32 s2, v248, 41
	v_readlane_b32 s3, v248, 42
	s_and_b64 vcc, exec, s[2:3]
	s_cbranch_vccz .LBB0_1291
	s_add_u32 s2, s0, 0x100000
	v_readlane_b32 s4, v248, 39
	s_addc_u32 s3, s1, 0
	v_lshlrev_b32_e32 v2, 3, v0
	v_readlane_b32 s12, v248, 7
	v_readlane_b32 s5, v248, 40
	s_mov_b32 s10, s4
	s_ashr_i32 s11, s4, 31
	v_readlane_b32 s14, v248, 9
	v_readlane_b32 s15, v248, 10
	v_add_u32_e32 v6, 0x200, v2
	v_add_u32_e32 v10, 0x400, v2
	v_add_u32_e32 v14, 0x600, v2
	s_lshl_b64 s[4:5], s[10:11], 12
	v_ashrrev_i32_e32 v3, 31, v2
	v_readlane_b32 s13, v248, 8
	s_mov_b64 s[6:7], s[14:15]
	v_ashrrev_i32_e32 v7, 31, v6
	v_ashrrev_i32_e32 v11, 31, v10
	v_ashrrev_i32_e32 v15, 31, v14
	s_add_u32 s12, s0, s4
	v_lshl_add_u64 v[32:33], v[2:3], 2, s[6:7]
	v_lshl_add_u64 v[34:35], v[6:7], 2, s[6:7]
	v_lshl_add_u64 v[36:37], v[10:11], 2, s[6:7]
	v_lshl_add_u64 v[38:39], v[14:15], 2, s[6:7]
	s_addc_u32 s13, s1, s5
	s_ashr_i32 s69, s68, 31
	v_readlane_b32 s4, v248, 3
	v_readlane_b32 s16, v248, 11
	v_or_b32_e32 v4, 4, v2
	v_add_u32_e32 v8, 0x204, v2
	v_add_u32_e32 v12, 0x404, v2
	v_add_u32_e32 v16, 0x604, v2
	s_lshl_b64 s[14:15], s[68:69], 12
	s_lshl_b64 s[0:1], s[10:11], 13
	v_readlane_b32 s6, v248, 5
	v_ashrrev_i32_e32 v1, 31, v0
	v_readlane_b32 s17, v248, 12
	v_readlane_b32 s18, v248, 13
	v_readlane_b32 s19, v248, 14
	v_ashrrev_i32_e32 v5, 31, v4
	v_ashrrev_i32_e32 v9, 31, v8
	v_ashrrev_i32_e32 v13, 31, v12
	v_ashrrev_i32_e32 v17, 31, v16
	v_readlane_b32 s5, v248, 4
	v_readlane_b32 s7, v248, 6
	s_add_u32 s16, s6, s0
	s_mov_b32 s0, s10
	v_lshlrev_b64 v[40:41], 4, v[0:1]
	s_addc_u32 s17, s7, s1
	s_lshl_b64 s[18:19], s[68:69], 13
	s_mov_b32 s4, 0xffff0000
	v_mov_b32_e32 v62, 0x358637bd
	s_mov_b32 s5, 0xf800000
	v_mov_b32_e32 v63, 0x260
	v_lshlrev_b64 v[42:43], 2, v[2:3]
	v_lshlrev_b64 v[44:45], 2, v[4:5]
	v_lshlrev_b64 v[46:47], 2, v[6:7]
	v_lshlrev_b64 v[48:49], 2, v[8:9]
	v_lshlrev_b64 v[50:51], 2, v[10:11]
	v_lshlrev_b64 v[52:53], 2, v[12:13]
	v_lshlrev_b64 v[54:55], 2, v[14:15]
	v_lshlrev_b64 v[56:57], 2, v[16:17]
	s_movk_i32 s6, 0x7fff
	s_mov_b32 s7, 0x7a00000
	v_writelane_b32 v248, s0, 39
	s_nop 1
	v_writelane_b32 v248, s1, 40
	s_add_u32 s100, s16, 0x8000000
	s_addc_u32 s101, s17, 0
	v_lshl_add_u64 v[226:227], s[100:101], 0, v[40:41]
	global_load_dwordx4 v[210:213], v[226:227], off offset:1024
	global_load_dwordx4 v[214:217], v[226:227], off offset:2048
	global_load_dwordx4 v[218:221], v[226:227], off offset:3072
	global_load_dwordx4 v[222:225], v[226:227], off
.LBB0_1290:
	global_load_dwordx4 v[0:3], v[32:33], off offset:16
	global_load_dwordx4 v[4:7], v[32:33], off
	global_load_dwordx4 v[8:11], v[32:33], off offset:2048
	global_load_dwordx4 v[12:15], v[34:35], off offset:16
	global_load_dwordx4 v[16:19], v[36:37], off offset:16
	global_load_dwordx4 v[20:23], v[36:37], off
	global_load_dwordx4 v[24:27], v[38:39], off offset:16
	global_load_dwordx4 v[28:31], v[38:39], off
	s_add_i32 s0, s10, 0x4000
	s_lshr_b32 s1, s10, 11
	v_lshl_add_u64 v[58:59], s[12:13], 0, v[40:41]
	s_ashr_i32 s11, s0, 12
	s_add_i32 s20, s1, 4
	v_add_co_u32_e64 v58, s[0:1], s7, v58
	s_cmp_lt_i32 s10, 0
	s_nop 0
	v_addc_co_u32_e64 v59, s[0:1], 0, v59, s[0:1]
	s_cselect_b32 s0, s11, s20
	s_mul_hi_i32 s1, s0, 0xc000
	s_mul_i32 s0, s0, 0xc000
	s_add_u32 s0, s2, s0
	s_addc_u32 s1, s3, s1
	s_add_u32 s20, s0, 0x8000
	s_addc_u32 s21, s1, 0
	v_lshl_add_u64 v[60:61], s[20:21], 0, v[42:43]
	v_lshl_add_u64 v[84:85], s[20:21], 0, v[44:45]
	v_lshl_add_u64 v[88:89], s[20:21], 0, v[46:47]
	v_lshl_add_u64 v[92:93], s[20:21], 0, v[48:49]
	v_lshl_add_u64 v[96:97], s[20:21], 0, v[50:51]
	v_lshl_add_u64 v[100:101], s[20:21], 0, v[52:53]
	v_lshl_add_u64 v[104:105], s[20:21], 0, v[54:55]
	v_lshl_add_u64 v[108:109], s[20:21], 0, v[56:57]
	flat_load_dwordx4 v[80:83], v[60:61]
	s_nop 0
	flat_load_dwordx4 v[84:87], v[84:85]
	s_nop 0
	flat_load_dwordx4 v[88:91], v[88:89]
	s_nop 0
	flat_load_dwordx4 v[92:95], v[92:93]
	s_nop 0
	flat_load_dwordx4 v[96:99], v[96:97]
	s_nop 0
	flat_load_dwordx4 v[100:103], v[100:101]
	s_nop 0
	flat_load_dwordx4 v[104:107], v[104:105]
	s_nop 0
	flat_load_dwordx4 v[108:111], v[108:109]
	s_add_u32 s0, s0, 0x6000
	s_addc_u32 s1, s1, 0
	v_lshl_add_u64 v[60:61], s[0:1], 0, v[42:43]
	v_lshl_add_u64 v[116:117], s[0:1], 0, v[44:45]
	v_lshl_add_u64 v[120:121], s[0:1], 0, v[46:47]
	v_lshl_add_u64 v[124:125], s[0:1], 0, v[48:49]
	v_lshl_add_u64 v[128:129], s[0:1], 0, v[50:51]
	v_lshl_add_u64 v[132:133], s[0:1], 0, v[52:53]
	v_lshl_add_u64 v[136:137], s[0:1], 0, v[54:55]
	v_lshl_add_u64 v[140:141], s[0:1], 0, v[56:57]
	flat_load_dwordx4 v[112:115], v[60:61]
	s_nop 0
	flat_load_dwordx4 v[116:119], v[116:117]
	s_nop 0
	flat_load_dwordx4 v[120:123], v[120:121]
	s_nop 0
	flat_load_dwordx4 v[124:127], v[124:125]
	s_nop 0
	flat_load_dwordx4 v[128:131], v[128:129]
	s_nop 0
	flat_load_dwordx4 v[132:135], v[132:133]
	s_nop 0
	flat_load_dwordx4 v[136:139], v[136:137]
	s_nop 0
	flat_load_dwordx4 v[140:143], v[140:141]
	s_add_i32 s10, s10, s68
	s_add_u32 s12, s12, s14
	s_addc_u32 s13, s13, s15
	s_add_u32 s16, s16, s18
	s_addc_u32 s17, s17, s19
	s_cmpk_lt_i32 s10, 0x4000
	s_waitcnt vmcnt(0)
	v_mov_b64_e32 v[64:65], v[210:211]
	v_mov_b64_e32 v[66:67], v[212:213]
	v_mov_b64_e32 v[68:69], v[214:215]
	v_mov_b64_e32 v[70:71], v[216:217]
	v_mov_b64_e32 v[72:73], v[218:219]
	v_mov_b64_e32 v[74:75], v[220:221]
	v_mov_b64_e32 v[76:77], v[222:223]
	v_mov_b64_e32 v[78:79], v[224:225]
	s_cmpk_lt_i32 s10, 0x4000
	s_cbranch_scc0 .Lg_nopf_1
	s_add_u32 s100, s16, 0x8000000
	s_addc_u32 s101, s17, 0
	v_lshl_add_u64 v[226:227], s[100:101], 0, v[40:41]
	global_load_dwordx4 v[210:213], v[226:227], off offset:1024
	global_load_dwordx4 v[214:217], v[226:227], off offset:2048
	global_load_dwordx4 v[218:221], v[226:227], off offset:3072
	global_load_dwordx4 v[222:225], v[226:227], off
; __device__ __forceinline__ float bf_lo(unsigned w) { return __uint_as_float(w << 16); }
; __device__ __forceinline__ float bf_hi(unsigned w) { return __uint_as_float(w & 0xffff0000u); }
; __device__ __forceinline__ float wave_sum(float v) {
; #pragma unroll
;     for (int o = 1; o < 64; o <<= 1) v += __shfl_xor(v, o);
;     return v;
; }
; template <bool MOD, bool SRC16>
; __device__ __forceinline__ void norm_rows(const float* src, int nrows, int tok0, const float* g, const float* ada, int sh_off, int sc_off, bf16* dst, float* dstf, int gw, int NGW, int lane_in) {
;     ...
;         if (SRC16) { const v4u* xh = (const v4u*)((const bf16*)src + (size_t)m * 4096) + lane;
; #pragma unroll
;             for (int j = 0; j < 4; ++j) { const v4u w = xh[64 * j]; v[2 * j] = (f32x4){pg8::bf_lo(w.x), pg8::bf_hi(w.x), pg8::bf_lo(w.y), pg8::bf_hi(w.y)}; v[2 * j + 1] = (f32x4){pg8::bf_lo(w.z), pg8::bf_hi(w.z), pg8::bf_lo(w.w), pg8::bf_hi(w.w)}; } }
;         else { const f32x4* xr = (const f32x4*)(src + (size_t)m * DM) + lane;
; #pragma unroll
;             for (int j = 0; j < 8; ++j) v[j] = __builtin_nontemporal_load(xr + 64 * j); }
; #pragma unroll
;         for (int j = 0; j < 8; ++j) { s += (v[j].x * v[j].x + v[j].y * v[j].y) + (v[j].z * v[j].z + v[j].w * v[j].w); }
;         const float r = 1.0f / sqrtf(wave_sum(s) * (1.f / DM) + EPS);
.Lg_nopf_1:
	v_lshlrev_b32_e32 v60, 16, v66
	v_and_b32_e32 v61, 0xffff0000, v66
	v_lshlrev_b32_e32 v66, 16, v68
	v_lshlrev_b32_e32 v147, 16, v78
	v_and_b32_e32 v149, 0xffff0000, v78
	v_and_b32_e32 v148, 0xffff0000, v76
	v_lshlrev_b32_e32 v151, 16, v79
	v_and_b32_e32 v79, 0xffff0000, v79
	v_and_b32_e32 v78, 0xffff0000, v77
	v_lshlrev_b32_e32 v146, 16, v76
	v_lshlrev_b32_e32 v150, 16, v77
	v_lshlrev_b32_e32 v77, 16, v65
	v_lshlrev_b32_e32 v76, 16, v64
	v_and_b32_e32 v65, 0xffff0000, v65
	v_and_b32_e32 v64, 0xffff0000, v64
	v_pk_mul_f32 v[158:159], v[148:149], v[148:149]
	v_pk_mul_f32 v[160:161], v[78:79], v[78:79]
	v_lshlrev_b32_e32 v152, 16, v67
	v_lshlrev_b32_e32 v155, 16, v71
	v_lshlrev_b32_e32 v154, 16, v70
	v_and_b32_e32 v71, 0xffff0000, v71
	v_and_b32_e32 v70, 0xffff0000, v70
	v_pk_mul_f32 v[162:163], v[64:65], v[64:65]
	v_mov_b32_e32 v178, v150
	v_mov_b32_e32 v179, v78
	v_mov_b32_e32 v180, v146
	v_mov_b32_e32 v181, v148
	v_mov_b32_e32 v78, v151
	v_mov_b32_e32 v148, v147
	v_pk_fma_f32 v[146:147], v[146:147], v[146:147], v[158:159]
	v_pk_fma_f32 v[150:151], v[150:151], v[150:151], v[160:161]
	v_and_b32_e32 v153, 0xffff0000, v67
	v_mul_f32_e32 v67, v60, v60
	v_mul_f32_e32 v165, v61, v61
	v_mul_f32_e32 v166, v152, v152
	v_mov_b32_e32 v164, v66
	v_pk_mul_f32 v[170:171], v[70:71], v[70:71]
	v_mov_b32_e32 v182, v77
	v_mov_b32_e32 v183, v65
	v_pk_fma_f32 v[158:159], v[76:77], v[76:77], v[162:163]
	v_mov_b32_e32 v77, v64
	v_pk_add_f32 v[64:65], v[146:147], v[150:151]
	v_and_b32_e32 v169, 0xffff0000, v68
	v_lshlrev_b32_e32 v68, 16, v69
	v_and_b32_e32 v69, 0xffff0000, v69
	v_mov_b32_e32 v184, v155
	v_mov_b32_e32 v185, v71
	v_pk_fma_f32 v[160:161], v[152:153], v[152:153], v[166:167] op_sel_hi:[1,1,0]
	v_pk_add_f32 v[162:163], v[66:67], v[164:165]
	v_pk_fma_f32 v[164:165], v[154:155], v[154:155], v[170:171]
	v_mov_b32_e32 v155, v70
	v_pk_add_f32 v[70:71], v[158:159], v[158:159] op_sel_hi:[0,1]
	v_pk_add_f32 v[64:65], v[64:65], v[64:65] op_sel_hi:[0,1]
	v_mul_f32_e32 v168, v66, v66
	v_mov_b32_e32 v67, v169
	v_mul_f32_e32 v160, v169, v169
	v_mov_b32_e32 v169, v163
	v_mul_f32_e32 v70, v69, v69
	v_mul_f32_e32 v64, v68, v68
	v_lshlrev_b32_e32 v144, 16, v72
	v_and_b32_e32 v145, 0xffff0000, v72
	v_lshlrev_b32_e32 v72, 16, v74
	v_lshlrev_b32_e32 v156, 16, v73
	v_pk_add_f32 v[150:151], v[168:169], v[160:161]
	v_pk_add_f32 v[64:65], v[64:65], v[70:71]
	v_and_b32_e32 v175, 0xffff0000, v74
	v_and_b32_e32 v157, 0xffff0000, v73
	v_mul_f32_e32 v73, v144, v144
	v_mul_f32_e32 v173, v145, v145
	v_mul_f32_e32 v174, v156, v156
	v_mov_b32_e32 v172, v72
	v_pk_add_f32 v[64:65], v[150:151], v[64:65]
	v_lshlrev_b32_e32 v74, 16, v75
	v_and_b32_e32 v75, 0xffff0000, v75
	v_pk_fma_f32 v[166:167], v[156:157], v[156:157], v[174:175] op_sel_hi:[1,1,0]
	v_pk_add_f32 v[170:171], v[72:73], v[172:173]
	v_pk_add_f32 v[146:147], v[164:165], v[164:165] op_sel_hi:[0,1]
	v_pk_add_f32 v[64:65], v[64:65], v[64:65] op_sel_hi:[0,1]
	v_mul_f32_e32 v176, v72, v72
	v_mul_f32_e32 v166, v175, v175
	v_mov_b32_e32 v177, v171
	v_mul_f32_e32 v146, v74, v74
	v_mul_f32_e32 v64, v75, v75
	v_pk_add_f32 v[158:159], v[176:177], v[166:167]
	v_pk_add_f32 v[64:65], v[146:147], v[64:65]
	s_waitcnt lgkmcnt(0)
	v_pk_add_f32 v[70:71], v[82:83], 1.0 op_sel_hi:[1,0]
	v_pk_add_f32 v[64:65], v[158:159], v[64:65]
	v_pk_add_f32 v[82:83], v[86:87], 1.0 op_sel_hi:[1,0]
	v_add_f32_e32 v64, v64, v65
	ds_bpermute_b32 v65, v195, v64
	v_pk_add_f32 v[86:87], v[90:91], 1.0 op_sel_hi:[1,0]
	v_pk_add_f32 v[90:91], v[94:95], 1.0 op_sel_hi:[1,0]
	v_pk_add_f32 v[94:95], v[98:99], 1.0 op_sel_hi:[1,0]
	v_pk_add_f32 v[98:99], v[102:103], 1.0 op_sel_hi:[1,0]
	s_waitcnt lgkmcnt(0)
	v_add_f32_e32 v64, v64, v65
	ds_bpermute_b32 v65, v202, v64
	v_pk_add_f32 v[102:103], v[106:107], 1.0 op_sel_hi:[1,0]
	v_pk_add_f32 v[106:107], v[110:111], 1.0 op_sel_hi:[1,0]
	v_mov_b32_e32 v73, v175
	v_pk_add_f32 v[80:81], v[80:81], 1.0 op_sel_hi:[1,0]
	s_waitcnt lgkmcnt(0)
	v_add_f32_e32 v64, v64, v65
	ds_bpermute_b32 v65, v203, v64
	v_pk_add_f32 v[84:85], v[84:85], 1.0 op_sel_hi:[1,0]
	v_pk_add_f32 v[88:89], v[88:89], 1.0 op_sel_hi:[1,0]
	v_pk_add_f32 v[92:93], v[92:93], 1.0 op_sel_hi:[1,0]
	v_pk_add_f32 v[96:97], v[96:97], 1.0 op_sel_hi:[1,0]
	s_waitcnt lgkmcnt(0)
	v_add_f32_e32 v64, v64, v65
	ds_bpermute_b32 v65, v204, v64
	v_pk_add_f32 v[100:101], v[100:101], 1.0 op_sel_hi:[1,0]
	v_pk_add_f32 v[104:105], v[104:105], 1.0 op_sel_hi:[1,0]
	v_pk_add_f32 v[108:109], v[108:109], 1.0 op_sel_hi:[1,0]
	s_waitcnt lgkmcnt(0)
	v_add_f32_e32 v64, v64, v65
	ds_bpermute_b32 v65, v205, v64
	s_waitcnt lgkmcnt(0)
	v_add_f32_e32 v64, v64, v65
	ds_bpermute_b32 v65, v206, v64
	s_waitcnt lgkmcnt(0)
; __device__ __forceinline__ unsigned pk2(float lo, float hi) { return f2bf(lo) | (f2bf(hi) << 16); }
; template <bool MOD, bool SRC16>
; __device__ __forceinline__ void norm_rows(const float* src, int nrows, int tok0, const float* g, const float* ada, int sh_off, int sc_off, bf16* dst, float* dstf, int gw, int NGW, int lane_in) {
;     ...
;         const float r = 1.0f / sqrtf(wave_sum(s) * (1.f / DM) + EPS);
;         if (MOD) {
;             const int b = batch_of(tok0 + m); const float* ab = ada + (size_t)b * ADAW;
;             f32x4 y[8];
; #pragma unroll
;             for (int j = 0; j < 8; ++j) { const int col = SRC16 ? 8 * (lane + 64 * (j >> 1)) + 4 * (j & 1) : 4 * (lane + 64 * j);
;                 const f32x4 gv = *(const f32x4*)(g + col), sc = *(const f32x4*)(ab + sc_off + col), sh = *(const f32x4*)(ab + sh_off + col);
;                 y[j] = (v[j] * r) * gv * (sc + 1.0f) + sh; }
;             if (SRC16) { v4u* o16 = (v4u*)(dst + (size_t)m * DM) + lane;
; #pragma unroll
;                 for (int j = 0; j < 4; ++j) { v4u w; w.x = pk2(y[2 * j].x, y[2 * j].y); w.y = pk2(y[2 * j].z, y[2 * j].w); w.z = pk2(y[2 * j + 1].x, y[2 * j + 1].y); w.w = pk2(y[2 * j + 1].z, y[2 * j + 1].w); o16[64 * j] = w; } }
	v_add_f32_e32 v64, v64, v65
	v_fmamk_f32 v64, v64, 0x3a000000, v62
	v_mul_f32_e32 v65, 0x4f800000, v64
	v_cmp_gt_f32_e32 vcc, s5, v64
	s_nop 1
	v_cndmask_b32_e32 v64, v64, v65, vcc
	v_sqrt_f32_e32 v65, v64
	s_nop 0
	v_add_u32_e32 v110, -1, v65
	v_add_u32_e32 v111, 1, v65
	v_fma_f32 v146, -v110, v65, v64
	v_fma_f32 v147, -v111, v65, v64
	v_cmp_ge_f32_e64 s[0:1], 0, v146
	s_nop 1
	v_cndmask_b32_e64 v65, v65, v110, s[0:1]
	v_cmp_lt_f32_e64 s[0:1], 0, v147
	s_nop 1
	v_cndmask_b32_e64 v65, v65, v111, s[0:1]
	v_mul_f32_e32 v110, 0x37800000, v65
	v_cndmask_b32_e32 v65, v65, v110, vcc
	v_cmp_class_f32_e32 vcc, v64, v63
	s_nop 1
	v_cndmask_b32_e32 v64, v65, v64, vcc
	v_div_scale_f32 v65, s[0:1], v64, v64, 1.0
	v_rcp_f32_e32 v111, v65
	v_div_scale_f32 v110, vcc, 1.0, v64, 1.0
	v_fma_f32 v146, -v65, v111, 1.0
	v_fmac_f32_e32 v111, v146, v111
	v_mul_f32_e32 v146, v110, v111
	v_fma_f32 v147, -v65, v146, v110
	v_fmac_f32_e32 v146, v147, v111
	v_fma_f32 v65, -v65, v146, v110
	v_div_fmas_f32 v65, v65, v111, v146
	v_div_fixup_f32 v64, v65, v64, 1.0
	v_pk_mul_f32 v[110:111], v[178:179], v[64:65] op_sel_hi:[1,0]
	v_pk_mul_f32 v[146:147], v[180:181], v[64:65] op_sel_hi:[1,0]
	v_pk_mul_f32 v[78:79], v[78:79], v[64:65] op_sel_hi:[1,0]
	v_pk_mul_f32 v[148:149], v[148:149], v[64:65] op_sel_hi:[1,0]
	v_pk_mul_f32 v[150:151], v[64:65], v[182:183] op_sel_hi:[0,1]
	v_pk_mul_f32 v[76:77], v[64:65], v[76:77] op_sel_hi:[0,1]
	v_pk_mul_f32 v[152:153], v[152:153], v[64:65] op_sel_hi:[1,0]
	v_pk_mul_f32 v[60:61], v[60:61], v[64:65] op_sel_hi:[1,0]
	v_pk_mul_f32 v[68:69], v[68:69], v[64:65] op_sel_hi:[1,0]
	v_pk_mul_f32 v[66:67], v[66:67], v[64:65] op_sel_hi:[1,0]
	v_pk_mul_f32 v[158:159], v[64:65], v[184:185] op_sel_hi:[0,1]
	v_pk_mul_f32 v[154:155], v[64:65], v[154:155] op_sel_hi:[0,1]
	v_pk_mul_f32 v[156:157], v[156:157], v[64:65] op_sel_hi:[1,0]
	v_pk_mul_f32 v[144:145], v[144:145], v[64:65] op_sel_hi:[1,0]
	v_pk_mul_f32 v[74:75], v[74:75], v[64:65] op_sel_hi:[1,0]
	v_pk_mul_f32 v[64:65], v[72:73], v[64:65] op_sel_hi:[1,0]
	v_pk_mul_f32 v[4:5], v[4:5], v[146:147]
	v_pk_mul_f32 v[6:7], v[6:7], v[110:111]
	v_pk_mul_f32 v[0:1], v[0:1], v[148:149]
	v_pk_mul_f32 v[2:3], v[2:3], v[78:79]
	v_pk_mul_f32 v[8:9], v[8:9], v[76:77]
	v_pk_mul_f32 v[10:11], v[10:11], v[150:151]
	v_pk_mul_f32 v[12:13], v[12:13], v[60:61]
	v_pk_mul_f32 v[14:15], v[14:15], v[152:153]
	v_pk_mul_f32 v[20:21], v[20:21], v[66:67]
	v_pk_mul_f32 v[22:23], v[22:23], v[68:69]
	v_pk_mul_f32 v[16:17], v[16:17], v[154:155]
	v_pk_mul_f32 v[18:19], v[18:19], v[158:159]
	v_pk_mul_f32 v[28:29], v[144:145], v[28:29]
	v_pk_mul_f32 v[30:31], v[156:157], v[30:31]
	v_pk_mul_f32 v[24:25], v[64:65], v[24:25]
	v_pk_mul_f32 v[26:27], v[74:75], v[26:27]
	v_pk_fma_f32 v[6:7], v[70:71], v[6:7], v[114:115]
	v_pk_fma_f32 v[4:5], v[80:81], v[4:5], v[112:113]
	v_pk_fma_f32 v[2:3], v[82:83], v[2:3], v[118:119]
	v_pk_fma_f32 v[0:1], v[84:85], v[0:1], v[116:117]
	v_pk_fma_f32 v[10:11], v[86:87], v[10:11], v[122:123]
	v_pk_fma_f32 v[8:9], v[88:89], v[8:9], v[120:121]
	v_pk_fma_f32 v[14:15], v[90:91], v[14:15], v[126:127]
	v_pk_fma_f32 v[12:13], v[92:93], v[12:13], v[124:125]
	v_pk_fma_f32 v[22:23], v[94:95], v[22:23], v[130:131]
	v_pk_fma_f32 v[20:21], v[96:97], v[20:21], v[128:129]
	v_pk_fma_f32 v[18:19], v[18:19], v[98:99], v[134:135]
	v_pk_fma_f32 v[16:17], v[16:17], v[100:101], v[132:133]
	v_pk_fma_f32 v[30:31], v[30:31], v[102:103], v[138:139]
	v_pk_fma_f32 v[28:29], v[28:29], v[104:105], v[136:137]
	v_pk_fma_f32 v[26:27], v[26:27], v[106:107], v[142:143]
	v_pk_fma_f32 v[24:25], v[24:25], v[108:109], v[140:141]
	v_bfe_u32 v60, v4, 16, 1
	v_bfe_u32 v64, v6, 16, 1
	v_bfe_u32 v66, v0, 16, 1
	v_bfe_u32 v67, v1, 16, 1
	v_bfe_u32 v68, v2, 16, 1
	v_bfe_u32 v61, v5, 16, 1
	v_bfe_u32 v65, v7, 16, 1
	v_bfe_u32 v69, v3, 16, 1
	v_bfe_u32 v70, v8, 16, 1
	v_bfe_u32 v71, v9, 16, 1
	v_bfe_u32 v72, v10, 16, 1
	v_bfe_u32 v73, v11, 16, 1
	v_bfe_u32 v74, v12, 16, 1
	v_bfe_u32 v75, v13, 16, 1
	v_bfe_u32 v76, v14, 16, 1
	v_bfe_u32 v77, v15, 16, 1
	v_bfe_u32 v78, v20, 16, 1
	v_bfe_u32 v79, v21, 16, 1
	v_bfe_u32 v80, v22, 16, 1
	v_bfe_u32 v81, v23, 16, 1
	v_bfe_u32 v82, v16, 16, 1
	v_bfe_u32 v84, v18, 16, 1
	v_bfe_u32 v86, v28, 16, 1
	v_bfe_u32 v87, v29, 16, 1
	v_bfe_u32 v88, v30, 16, 1
	v_bfe_u32 v89, v31, 16, 1
	v_bfe_u32 v90, v24, 16, 1
	v_bfe_u32 v92, v26, 16, 1
	v_add3_u32 v4, v4, v60, s6
	v_add3_u32 v6, v6, v64, s6
	v_add3_u32 v0, v0, v66, s6
	v_add3_u32 v60, v1, v67, s6
	v_add3_u32 v1, v2, v68, s6
	v_bfe_u32 v83, v17, 16, 1
	v_bfe_u32 v85, v19, 16, 1
	v_bfe_u32 v91, v25, 16, 1
	v_bfe_u32 v93, v27, 16, 1
	v_add3_u32 v5, v5, v61, s6
	v_add3_u32 v7, v7, v65, s6
	v_add3_u32 v3, v3, v69, s6
	v_add3_u32 v2, v8, v70, s6
	v_add3_u32 v8, v9, v71, s6
	v_add3_u32 v9, v10, v72, s6
	v_add3_u32 v10, v11, v73, s6
	v_add3_u32 v11, v12, v74, s6
	v_add3_u32 v12, v13, v75, s6
	v_add3_u32 v13, v14, v76, s6
	v_add3_u32 v14, v15, v77, s6
	v_add3_u32 v15, v20, v78, s6
	v_add3_u32 v20, v21, v79, s6
	v_add3_u32 v21, v22, v80, s6
	v_add3_u32 v22, v23, v81, s6
	v_add3_u32 v16, v16, v82, s6
	v_add3_u32 v18, v18, v84, s6
	v_add3_u32 v23, v28, v86, s6
	v_add3_u32 v28, v29, v87, s6
	v_add3_u32 v29, v30, v88, s6
	v_add3_u32 v30, v31, v89, s6
	v_add3_u32 v24, v24, v90, s6
	v_add3_u32 v26, v26, v92, s6
	v_lshrrev_b32_e32 v4, 16, v4
	v_lshrrev_b32_e32 v6, 16, v6
	v_lshrrev_b32_e32 v31, 16, v0
	v_lshrrev_b32_e32 v61, 16, v1
	v_add3_u32 v17, v17, v83, s6
	v_add3_u32 v19, v19, v85, s6
	v_add3_u32 v25, v25, v91, s6
	v_add3_u32 v27, v27, v93, s6
	v_lshrrev_b32_e32 v64, 16, v2
	v_lshrrev_b32_e32 v9, 16, v9
	v_lshrrev_b32_e32 v11, 16, v11
	v_lshrrev_b32_e32 v13, 16, v13
	v_lshrrev_b32_e32 v15, 16, v15
	v_lshrrev_b32_e32 v21, 16, v21
	v_lshrrev_b32_e32 v16, 16, v16
	v_lshrrev_b32_e32 v18, 16, v18
	v_lshrrev_b32_e32 v23, 16, v23
	v_lshrrev_b32_e32 v29, 16, v29
	v_lshrrev_b32_e32 v24, 16, v24
	v_lshrrev_b32_e32 v26, 16, v26
	v_and_or_b32 v0, v5, s4, v4
	v_and_or_b32 v1, v7, s4, v6
	v_and_or_b32 v2, v60, s4, v31
	v_and_or_b32 v3, v3, s4, v61
	v_and_or_b32 v4, v8, s4, v64
	v_and_or_b32 v5, v10, s4, v9
	v_and_or_b32 v6, v12, s4, v11
	v_and_or_b32 v7, v14, s4, v13
	v_and_or_b32 v8, v20, s4, v15
	v_and_or_b32 v9, v22, s4, v21
	v_and_or_b32 v10, v17, s4, v16
	v_and_or_b32 v11, v19, s4, v18
	v_and_or_b32 v12, v28, s4, v23
	v_and_or_b32 v13, v30, s4, v29
	v_and_or_b32 v14, v25, s4, v24
	v_and_or_b32 v15, v27, s4, v26
	flat_store_dwordx4 v[58:59], v[0:3]
	flat_store_dwordx4 v[58:59], v[4:7] offset:1024
	flat_store_dwordx4 v[58:59], v[8:11] offset:2048
	flat_store_dwordx4 v[58:59], v[12:15] offset:3072
	s_cmpk_lt_i32 s10, 0x4000
	s_cbranch_scc1 .LBB0_1290

; __device__ __forceinline__ float bf_lo(unsigned w) { return __uint_as_float(w << 16); }
; __device__ __forceinline__ float bf_hi(unsigned w) { return __uint_as_float(w & 0xffff0000u); }
; template <bool MOD, bool SRC16>
; __device__ __forceinline__ void norm_rows(const float* src, int nrows, int tok0, const float* g, const float* ada, int sh_off, int sc_off, bf16* dst, float* dstf, int gw, int NGW, int lane_in) {
;     ...
;     for (int m = gw; m < nrows; m += NGW) {
;         f32x4 v[8]; float s = 0.f;
;         if (SRC16) { const v4u* xh = (const v4u*)((const bf16*)src + (size_t)m * 4096) + lane;
; #pragma unroll
;             for (int j = 0; j < 4; ++j) { const v4u w = xh[64 * j]; v[2 * j] = (f32x4){pg8::bf_lo(w.x), pg8::bf_hi(w.x), pg8::bf_lo(w.y), pg8::bf_hi(w.y)}; v[2 * j + 1] = (f32x4){pg8::bf_lo(w.z), pg8::bf_hi(w.z), pg8::bf_lo(w.w), pg8::bf_hi(w.w)}; } }
;         else { const f32x4* xr = (const f32x4*)(src + (size_t)m * DM) + lane;
; #pragma unroll
;             for (int j = 0; j < 8; ++j) v[j] = __builtin_nontemporal_load(xr + 64 * j); }
; #pragma unroll
;         for (int j = 0; j < 8; ++j) { s += (v[j].x * v[j].x + v[j].y * v[j].y) + (v[j].z * v[j].z + v[j].w * v[j].w); }
;         const float r = 1.0f / sqrtf(wave_sum(s) * (1.f / DM) + EPS);
;         if (MOD) {
;             const int b = batch_of(tok0 + m); const float* ab = ada + (size_t)b * ADAW;
;             f32x4 y[8];
; #pragma unroll
;             for (int j = 0; j < 8; ++j) { const int col = SRC16 ? 8 * (lane + 64 * (j >> 1)) + 4 * (j & 1) : 4 * (lane + 64 * j);
;                 const f32x4 gv = *(const f32x4*)(g + col), sc = *(const f32x4*)(ab + sc_off + col), sh = *(const f32x4*)(ab + sh_off + col);
;                 y[j] = (v[j] * r) * gv * (sc + 1.0f) + sh; }
.LBB0_1944:
	s_or_b64 exec, exec, s[0:1]
	v_readlane_b32 s0, v248, 1
	v_readlane_b32 s1, v248, 2
	s_mov_b32 s2, s82
	s_mov_b32 s3, s91
	s_waitcnt lgkmcnt(0)
	s_barrier
	v_mov_b32_e32 v0, v192
	v_readlane_b32 s2, v248, 41
	v_readlane_b32 s3, v248, 42
	s_and_b64 vcc, exec, s[2:3]
	s_cbranch_vccz .LBB0_1947
	v_lshlrev_b32_e32 v2, 3, v0
	v_readlane_b32 s8, v248, 7
	v_readlane_b32 s10, v248, 9
	v_readlane_b32 s11, v248, 10
	v_add_u32_e32 v6, 0x200, v2
	v_add_u32_e32 v10, 0x400, v2
	v_add_u32_e32 v14, 0x600, v2
	v_ashrrev_i32_e32 v3, 31, v2
	s_mov_b64 s[6:7], s[10:11]
	v_ashrrev_i32_e32 v7, 31, v6
	v_ashrrev_i32_e32 v11, 31, v10
	v_ashrrev_i32_e32 v15, 31, v14
	s_add_u32 s2, s0, 0x100000
	v_lshl_add_u64 v[32:33], v[2:3], 2, s[6:7]
	v_lshl_add_u64 v[34:35], v[6:7], 2, s[6:7]
	v_lshl_add_u64 v[36:37], v[10:11], 2, s[6:7]
	v_lshl_add_u64 v[38:39], v[14:15], 2, s[6:7]
	v_readlane_b32 s6, v248, 39
	s_addc_u32 s3, s1, 0
	v_readlane_b32 s7, v248, 40
	s_mov_b32 s18, s6
	s_ashr_i32 s19, s6, 31
	s_lshl_b64 s[6:7], s[18:19], 12
	v_readlane_b32 s12, v248, 11
	v_readlane_b32 s13, v248, 12
	v_readlane_b32 s14, v248, 13
	v_readlane_b32 s15, v248, 14
	s_add_u32 s6, s0, s6
	v_readlane_b32 s9, v248, 8
	s_addc_u32 s7, s1, s7
	s_ashr_i32 s87, s86, 31
	v_readlane_b32 s12, v248, 3
	v_or_b32_e32 v4, 4, v2
	v_add_u32_e32 v8, 0x204, v2
	v_add_u32_e32 v12, 0x404, v2
	v_add_u32_e32 v16, 0x604, v2
	s_lshl_b64 s[8:9], s[86:87], 12
	s_lshl_b64 s[0:1], s[18:19], 13
	v_readlane_b32 s14, v248, 5
	v_ashrrev_i32_e32 v1, 31, v0
	v_ashrrev_i32_e32 v5, 31, v4
	v_ashrrev_i32_e32 v9, 31, v8
	v_ashrrev_i32_e32 v13, 31, v12
	v_ashrrev_i32_e32 v17, 31, v16
	v_readlane_b32 s13, v248, 4
	v_readlane_b32 s15, v248, 6
	s_add_u32 s12, s14, s0
	s_mov_b32 s0, s18
	v_lshlrev_b64 v[40:41], 4, v[0:1]
	s_addc_u32 s13, s15, s1
	s_lshl_b64 s[14:15], s[86:87], 13
	s_mov_b32 s10, 0xffff0000
	v_mov_b32_e32 v62, 0x358637bd
	s_mov_b32 s11, 0xf800000
	v_mov_b32_e32 v63, 0x260
	v_lshlrev_b64 v[42:43], 2, v[2:3]
	v_lshlrev_b64 v[44:45], 2, v[4:5]
	v_lshlrev_b64 v[46:47], 2, v[6:7]
	v_lshlrev_b64 v[48:49], 2, v[8:9]
	v_lshlrev_b64 v[50:51], 2, v[10:11]
	v_lshlrev_b64 v[52:53], 2, v[12:13]
	v_lshlrev_b64 v[54:55], 2, v[14:15]
	v_lshlrev_b64 v[56:57], 2, v[16:17]
	s_movk_i32 s16, 0x7fff
	s_mov_b32 s17, 0x7a00000
	v_writelane_b32 v248, s0, 39
	s_nop 1
	v_writelane_b32 v248, s1, 40
	s_add_u32 s100, s12, 0x10000000
	s_addc_u32 s101, s13, 0
	v_lshl_add_u64 v[226:227], s[100:101], 0, v[40:41]
	global_load_dwordx4 v[210:213], v[226:227], off offset:1024
	global_load_dwordx4 v[214:217], v[226:227], off offset:2048
	global_load_dwordx4 v[218:221], v[226:227], off offset:3072
	global_load_dwordx4 v[222:225], v[226:227], off
.LBB0_1946:
	global_load_dwordx4 v[0:3], v[32:33], off offset:16
	global_load_dwordx4 v[4:7], v[32:33], off
	global_load_dwordx4 v[8:11], v[32:33], off offset:2048
	global_load_dwordx4 v[12:15], v[34:35], off offset:16
	global_load_dwordx4 v[16:19], v[36:37], off offset:16
	global_load_dwordx4 v[20:23], v[36:37], off
	global_load_dwordx4 v[24:27], v[38:39], off offset:16
	global_load_dwordx4 v[28:31], v[38:39], off
	s_add_i32 s1, s18, 0x4000
	s_add_i32 s0, s18, 0x8000
	v_lshl_add_u64 v[58:59], s[6:7], 0, v[40:41]
	s_lshr_b32 s20, s1, 11
	s_ashr_i32 s19, s0, 12
	v_add_co_u32_e64 v58, s[0:1], s17, v58
	s_add_i32 s20, s20, 4
	s_nop 0
	v_addc_co_u32_e64 v59, s[0:1], 0, v59, s[0:1]
	s_cmpk_lt_i32 s18, 0xc000
	s_cselect_b32 s0, s19, s20
	s_mul_hi_i32 s1, s0, 0xc000
	s_mul_i32 s0, s0, 0xc000
	s_add_u32 s0, s2, s0
	s_addc_u32 s1, s3, s1
	s_add_u32 s20, s0, 0x8000
	s_addc_u32 s21, s1, 0
	v_lshl_add_u64 v[60:61], s[20:21], 0, v[42:43]
	v_lshl_add_u64 v[104:105], s[20:21], 0, v[44:45]
	v_lshl_add_u64 v[106:107], s[20:21], 0, v[46:47]
	v_lshl_add_u64 v[108:109], s[20:21], 0, v[48:49]
	v_lshl_add_u64 v[110:111], s[20:21], 0, v[50:51]
	v_lshl_add_u64 v[112:113], s[20:21], 0, v[52:53]
	v_lshl_add_u64 v[114:115], s[20:21], 0, v[54:55]
	v_lshl_add_u64 v[116:117], s[20:21], 0, v[56:57]
	flat_load_dwordx4 v[80:83], v[60:61]
	flat_load_dwordx4 v[84:87], v[104:105]
	flat_load_dwordx4 v[88:91], v[106:107]
	flat_load_dwordx4 v[92:95], v[108:109]
	flat_load_dwordx4 v[96:99], v[110:111]
	flat_load_dwordx4 v[100:103], v[112:113]
	s_nop 0
	flat_load_dwordx4 v[104:107], v[114:115]
	flat_load_dwordx4 v[108:111], v[116:117]
	s_add_u32 s0, s0, 0x6000
	s_addc_u32 s1, s1, 0
	v_lshl_add_u64 v[60:61], s[0:1], 0, v[42:43]
	v_lshl_add_u64 v[116:117], s[0:1], 0, v[44:45]
	v_lshl_add_u64 v[120:121], s[0:1], 0, v[46:47]
	v_lshl_add_u64 v[124:125], s[0:1], 0, v[48:49]
	v_lshl_add_u64 v[128:129], s[0:1], 0, v[50:51]
	v_lshl_add_u64 v[132:133], s[0:1], 0, v[52:53]
	v_lshl_add_u64 v[136:137], s[0:1], 0, v[54:55]
	v_lshl_add_u64 v[140:141], s[0:1], 0, v[56:57]
	flat_load_dwordx4 v[112:115], v[60:61]
	s_nop 0
	flat_load_dwordx4 v[116:119], v[116:117]
	s_nop 0
	flat_load_dwordx4 v[120:123], v[120:121]
	s_nop 0
	flat_load_dwordx4 v[124:127], v[124:125]
	s_nop 0
	flat_load_dwordx4 v[128:131], v[128:129]
	s_nop 0
	flat_load_dwordx4 v[132:135], v[132:133]
	s_nop 0
	flat_load_dwordx4 v[136:139], v[136:137]
	s_nop 0
	flat_load_dwordx4 v[140:143], v[140:141]
	s_add_i32 s18, s18, s86
	s_add_u32 s6, s6, s8
	s_addc_u32 s7, s7, s9
	s_add_u32 s12, s12, s14
	s_addc_u32 s13, s13, s15
	s_cmpk_lt_i32 s18, 0x4000
	s_waitcnt vmcnt(0)
	v_mov_b64_e32 v[64:65], v[210:211]
	v_mov_b64_e32 v[66:67], v[212:213]
	v_mov_b64_e32 v[68:69], v[214:215]
	v_mov_b64_e32 v[70:71], v[216:217]
	v_mov_b64_e32 v[72:73], v[218:219]
	v_mov_b64_e32 v[74:75], v[220:221]
	v_mov_b64_e32 v[76:77], v[222:223]
	v_mov_b64_e32 v[78:79], v[224:225]
	s_cmpk_lt_i32 s18, 0x4000
	s_cbranch_scc0 .Lg_nopf_2
	s_add_u32 s100, s12, 0x10000000
	s_addc_u32 s101, s13, 0
	v_lshl_add_u64 v[226:227], s[100:101], 0, v[40:41]
	global_load_dwordx4 v[210:213], v[226:227], off offset:1024
	global_load_dwordx4 v[214:217], v[226:227], off offset:2048
	global_load_dwordx4 v[218:221], v[226:227], off offset:3072
	global_load_dwordx4 v[222:225], v[226:227], off
; __device__ __forceinline__ float bf_lo(unsigned w) { return __uint_as_float(w << 16); }
; __device__ __forceinline__ float bf_hi(unsigned w) { return __uint_as_float(w & 0xffff0000u); }
; __device__ __forceinline__ float wave_sum(float v) {
; #pragma unroll
;     for (int o = 1; o < 64; o <<= 1) v += __shfl_xor(v, o);
;     return v;
; }
; template <bool MOD, bool SRC16>
; __device__ __forceinline__ void norm_rows(const float* src, int nrows, int tok0, const float* g, const float* ada, int sh_off, int sc_off, bf16* dst, float* dstf, int gw, int NGW, int lane_in) {
;     ...
;         if (SRC16) { const v4u* xh = (const v4u*)((const bf16*)src + (size_t)m * 4096) + lane;
; #pragma unroll
;             for (int j = 0; j < 4; ++j) { const v4u w = xh[64 * j]; v[2 * j] = (f32x4){pg8::bf_lo(w.x), pg8::bf_hi(w.x), pg8::bf_lo(w.y), pg8::bf_hi(w.y)}; v[2 * j + 1] = (f32x4){pg8::bf_lo(w.z), pg8::bf_hi(w.z), pg8::bf_lo(w.w), pg8::bf_hi(w.w)}; } }
;         else { const f32x4* xr = (const f32x4*)(src + (size_t)m * DM) + lane;
; #pragma unroll
;             for (int j = 0; j < 8; ++j) v[j] = __builtin_nontemporal_load(xr + 64 * j); }
; #pragma unroll
;         for (int j = 0; j < 8; ++j) { s += (v[j].x * v[j].x + v[j].y * v[j].y) + (v[j].z * v[j].z + v[j].w * v[j].w); }
;         const float r = 1.0f / sqrtf(wave_sum(s) * (1.f / DM) + EPS);
.Lg_nopf_2:
	v_lshlrev_b32_e32 v60, 16, v66
	v_and_b32_e32 v61, 0xffff0000, v66
	v_lshlrev_b32_e32 v66, 16, v68
	v_lshlrev_b32_e32 v147, 16, v78
	v_and_b32_e32 v149, 0xffff0000, v78
	v_and_b32_e32 v148, 0xffff0000, v76
	v_lshlrev_b32_e32 v151, 16, v79
	v_and_b32_e32 v79, 0xffff0000, v79
	v_and_b32_e32 v78, 0xffff0000, v77
	v_lshlrev_b32_e32 v146, 16, v76
	v_lshlrev_b32_e32 v150, 16, v77
	v_lshlrev_b32_e32 v77, 16, v65
	v_lshlrev_b32_e32 v76, 16, v64
	v_and_b32_e32 v65, 0xffff0000, v65
	v_and_b32_e32 v64, 0xffff0000, v64
	v_pk_mul_f32 v[158:159], v[148:149], v[148:149]
	v_pk_mul_f32 v[160:161], v[78:79], v[78:79]
	v_lshlrev_b32_e32 v152, 16, v67
	v_lshlrev_b32_e32 v155, 16, v71
	v_lshlrev_b32_e32 v154, 16, v70
	v_and_b32_e32 v71, 0xffff0000, v71
	v_and_b32_e32 v70, 0xffff0000, v70
	v_pk_mul_f32 v[162:163], v[64:65], v[64:65]
	v_mov_b32_e32 v178, v150
	v_mov_b32_e32 v179, v78
	v_mov_b32_e32 v180, v146
	v_mov_b32_e32 v181, v148
	v_mov_b32_e32 v78, v151
	v_mov_b32_e32 v148, v147
	v_pk_fma_f32 v[146:147], v[146:147], v[146:147], v[158:159]
	v_pk_fma_f32 v[150:151], v[150:151], v[150:151], v[160:161]
	v_and_b32_e32 v153, 0xffff0000, v67
	v_mul_f32_e32 v67, v60, v60
	v_mul_f32_e32 v165, v61, v61
	v_mul_f32_e32 v166, v152, v152
	v_mov_b32_e32 v164, v66
	v_pk_mul_f32 v[170:171], v[70:71], v[70:71]
	v_mov_b32_e32 v182, v77
	v_mov_b32_e32 v183, v65
	v_pk_fma_f32 v[158:159], v[76:77], v[76:77], v[162:163]
	v_mov_b32_e32 v77, v64
	v_pk_add_f32 v[64:65], v[146:147], v[150:151]
	v_and_b32_e32 v169, 0xffff0000, v68
	v_lshlrev_b32_e32 v68, 16, v69
	v_and_b32_e32 v69, 0xffff0000, v69
	v_mov_b32_e32 v184, v155
	v_mov_b32_e32 v185, v71
	v_pk_fma_f32 v[160:161], v[152:153], v[152:153], v[166:167] op_sel_hi:[1,1,0]
	v_pk_add_f32 v[162:163], v[66:67], v[164:165]
	v_pk_fma_f32 v[164:165], v[154:155], v[154:155], v[170:171]
	v_mov_b32_e32 v155, v70
	v_pk_add_f32 v[70:71], v[158:159], v[158:159] op_sel_hi:[0,1]
	v_pk_add_f32 v[64:65], v[64:65], v[64:65] op_sel_hi:[0,1]
	v_mul_f32_e32 v168, v66, v66
	v_mov_b32_e32 v67, v169
	v_mul_f32_e32 v160, v169, v169
	v_mov_b32_e32 v169, v163
	v_mul_f32_e32 v70, v69, v69
	v_mul_f32_e32 v64, v68, v68
	v_lshlrev_b32_e32 v144, 16, v72
	v_and_b32_e32 v145, 0xffff0000, v72
	v_lshlrev_b32_e32 v72, 16, v74
	v_lshlrev_b32_e32 v156, 16, v73
	v_pk_add_f32 v[150:151], v[168:169], v[160:161]
	v_pk_add_f32 v[64:65], v[64:65], v[70:71]
	v_and_b32_e32 v175, 0xffff0000, v74
	v_and_b32_e32 v157, 0xffff0000, v73
	v_mul_f32_e32 v73, v144, v144
	v_mul_f32_e32 v173, v145, v145
	v_mul_f32_e32 v174, v156, v156
	v_mov_b32_e32 v172, v72
	v_pk_add_f32 v[64:65], v[150:151], v[64:65]
	v_lshlrev_b32_e32 v74, 16, v75
	v_and_b32_e32 v75, 0xffff0000, v75
	v_pk_fma_f32 v[166:167], v[156:157], v[156:157], v[174:175] op_sel_hi:[1,1,0]
	v_pk_add_f32 v[170:171], v[72:73], v[172:173]
	v_pk_add_f32 v[146:147], v[164:165], v[164:165] op_sel_hi:[0,1]
	v_pk_add_f32 v[64:65], v[64:65], v[64:65] op_sel_hi:[0,1]
	v_mul_f32_e32 v176, v72, v72
	v_mul_f32_e32 v166, v175, v175
	v_mov_b32_e32 v177, v171
	v_mul_f32_e32 v146, v74, v74
	v_mul_f32_e32 v64, v75, v75
	v_pk_add_f32 v[158:159], v[176:177], v[166:167]
	v_pk_add_f32 v[64:65], v[146:147], v[64:65]
	s_waitcnt lgkmcnt(0)
	v_pk_add_f32 v[70:71], v[82:83], 1.0 op_sel_hi:[1,0]
	v_pk_add_f32 v[64:65], v[158:159], v[64:65]
	v_pk_add_f32 v[82:83], v[86:87], 1.0 op_sel_hi:[1,0]
	v_add_f32_e32 v64, v64, v65
	ds_bpermute_b32 v65, v195, v64
	v_pk_add_f32 v[86:87], v[90:91], 1.0 op_sel_hi:[1,0]
	v_pk_add_f32 v[90:91], v[94:95], 1.0 op_sel_hi:[1,0]
	v_pk_add_f32 v[94:95], v[98:99], 1.0 op_sel_hi:[1,0]
	v_pk_add_f32 v[98:99], v[102:103], 1.0 op_sel_hi:[1,0]
	s_waitcnt lgkmcnt(0)
	v_add_f32_e32 v64, v64, v65
	ds_bpermute_b32 v65, v202, v64
	v_pk_add_f32 v[102:103], v[106:107], 1.0 op_sel_hi:[1,0]
	v_pk_add_f32 v[106:107], v[110:111], 1.0 op_sel_hi:[1,0]
	v_mov_b32_e32 v73, v175
	v_pk_add_f32 v[80:81], v[80:81], 1.0 op_sel_hi:[1,0]
	s_waitcnt lgkmcnt(0)
	v_add_f32_e32 v64, v64, v65
	ds_bpermute_b32 v65, v203, v64
	v_pk_add_f32 v[84:85], v[84:85], 1.0 op_sel_hi:[1,0]
	v_pk_add_f32 v[88:89], v[88:89], 1.0 op_sel_hi:[1,0]
	v_pk_add_f32 v[92:93], v[92:93], 1.0 op_sel_hi:[1,0]
	v_pk_add_f32 v[96:97], v[96:97], 1.0 op_sel_hi:[1,0]
	s_waitcnt lgkmcnt(0)
	v_add_f32_e32 v64, v64, v65
	ds_bpermute_b32 v65, v204, v64
	v_pk_add_f32 v[100:101], v[100:101], 1.0 op_sel_hi:[1,0]
	v_pk_add_f32 v[104:105], v[104:105], 1.0 op_sel_hi:[1,0]
	v_pk_add_f32 v[108:109], v[108:109], 1.0 op_sel_hi:[1,0]
	s_waitcnt lgkmcnt(0)
	v_add_f32_e32 v64, v64, v65
	ds_bpermute_b32 v65, v205, v64
	s_waitcnt lgkmcnt(0)
	v_add_f32_e32 v64, v64, v65
	ds_bpermute_b32 v65, v206, v64
	s_waitcnt lgkmcnt(0)
; __device__ __forceinline__ unsigned pk2(float lo, float hi) { return f2bf(lo) | (f2bf(hi) << 16); }
; template <bool MOD, bool SRC16>
; __device__ __forceinline__ void norm_rows(const float* src, int nrows, int tok0, const float* g, const float* ada, int sh_off, int sc_off, bf16* dst, float* dstf, int gw, int NGW, int lane_in) {
;     ...
;         const float r = 1.0f / sqrtf(wave_sum(s) * (1.f / DM) + EPS);
;         if (MOD) {
;             const int b = batch_of(tok0 + m); const float* ab = ada + (size_t)b * ADAW;
;             f32x4 y[8];
; #pragma unroll
;             for (int j = 0; j < 8; ++j) { const int col = SRC16 ? 8 * (lane + 64 * (j >> 1)) + 4 * (j & 1) : 4 * (lane + 64 * j);
;                 const f32x4 gv = *(const f32x4*)(g + col), sc = *(const f32x4*)(ab + sc_off + col), sh = *(const f32x4*)(ab + sh_off + col);
;                 y[j] = (v[j] * r) * gv * (sc + 1.0f) + sh; }
;             if (SRC16) { v4u* o16 = (v4u*)(dst + (size_t)m * DM) + lane;
; #pragma unroll
;                 for (int j = 0; j < 4; ++j) { v4u w; w.x = pk2(y[2 * j].x, y[2 * j].y); w.y = pk2(y[2 * j].z, y[2 * j].w); w.z = pk2(y[2 * j + 1].x, y[2 * j + 1].y); w.w = pk2(y[2 * j + 1].z, y[2 * j + 1].w); o16[64 * j] = w; } }
	v_add_f32_e32 v64, v64, v65
	v_fmamk_f32 v64, v64, 0x3a000000, v62
	v_mul_f32_e32 v65, 0x4f800000, v64
	v_cmp_gt_f32_e32 vcc, s11, v64
	s_nop 1
	v_cndmask_b32_e32 v64, v64, v65, vcc
	v_sqrt_f32_e32 v65, v64
	s_nop 0
	v_add_u32_e32 v110, -1, v65
	v_add_u32_e32 v111, 1, v65
	v_fma_f32 v146, -v110, v65, v64
	v_fma_f32 v147, -v111, v65, v64
	v_cmp_ge_f32_e64 s[0:1], 0, v146
	s_nop 1
	v_cndmask_b32_e64 v65, v65, v110, s[0:1]
	v_cmp_lt_f32_e64 s[0:1], 0, v147
	s_nop 1
	v_cndmask_b32_e64 v65, v65, v111, s[0:1]
	v_mul_f32_e32 v110, 0x37800000, v65
	v_cndmask_b32_e32 v65, v65, v110, vcc
	v_cmp_class_f32_e32 vcc, v64, v63
	s_nop 1
	v_cndmask_b32_e32 v64, v65, v64, vcc
	v_div_scale_f32 v65, s[0:1], v64, v64, 1.0
	v_rcp_f32_e32 v111, v65
	v_div_scale_f32 v110, vcc, 1.0, v64, 1.0
	v_fma_f32 v146, -v65, v111, 1.0
	v_fmac_f32_e32 v111, v146, v111
	v_mul_f32_e32 v146, v110, v111
	v_fma_f32 v147, -v65, v146, v110
	v_fmac_f32_e32 v146, v147, v111
	v_fma_f32 v65, -v65, v146, v110
	v_div_fmas_f32 v65, v65, v111, v146
	v_div_fixup_f32 v64, v65, v64, 1.0
	v_pk_mul_f32 v[110:111], v[178:179], v[64:65] op_sel_hi:[1,0]
	v_pk_mul_f32 v[146:147], v[180:181], v[64:65] op_sel_hi:[1,0]
	v_pk_mul_f32 v[78:79], v[78:79], v[64:65] op_sel_hi:[1,0]
	v_pk_mul_f32 v[148:149], v[148:149], v[64:65] op_sel_hi:[1,0]
	v_pk_mul_f32 v[150:151], v[64:65], v[182:183] op_sel_hi:[0,1]
	v_pk_mul_f32 v[76:77], v[64:65], v[76:77] op_sel_hi:[0,1]
	v_pk_mul_f32 v[152:153], v[152:153], v[64:65] op_sel_hi:[1,0]
	v_pk_mul_f32 v[60:61], v[60:61], v[64:65] op_sel_hi:[1,0]
	v_pk_mul_f32 v[68:69], v[68:69], v[64:65] op_sel_hi:[1,0]
	v_pk_mul_f32 v[66:67], v[66:67], v[64:65] op_sel_hi:[1,0]
	v_pk_mul_f32 v[158:159], v[64:65], v[184:185] op_sel_hi:[0,1]
	v_pk_mul_f32 v[154:155], v[64:65], v[154:155] op_sel_hi:[0,1]
	v_pk_mul_f32 v[156:157], v[156:157], v[64:65] op_sel_hi:[1,0]
	v_pk_mul_f32 v[144:145], v[144:145], v[64:65] op_sel_hi:[1,0]
	v_pk_mul_f32 v[74:75], v[74:75], v[64:65] op_sel_hi:[1,0]
	v_pk_mul_f32 v[64:65], v[72:73], v[64:65] op_sel_hi:[1,0]
	v_pk_mul_f32 v[4:5], v[4:5], v[146:147]
	v_pk_mul_f32 v[6:7], v[6:7], v[110:111]
	v_pk_mul_f32 v[0:1], v[0:1], v[148:149]
	v_pk_mul_f32 v[2:3], v[2:3], v[78:79]
	v_pk_mul_f32 v[8:9], v[8:9], v[76:77]
	v_pk_mul_f32 v[10:11], v[10:11], v[150:151]
	v_pk_mul_f32 v[12:13], v[12:13], v[60:61]
	v_pk_mul_f32 v[14:15], v[14:15], v[152:153]
	v_pk_mul_f32 v[20:21], v[20:21], v[66:67]
	v_pk_mul_f32 v[22:23], v[22:23], v[68:69]
	v_pk_mul_f32 v[16:17], v[16:17], v[154:155]
	v_pk_mul_f32 v[18:19], v[18:19], v[158:159]
	v_pk_mul_f32 v[28:29], v[144:145], v[28:29]
	v_pk_mul_f32 v[30:31], v[156:157], v[30:31]
	v_pk_mul_f32 v[24:25], v[64:65], v[24:25]
	v_pk_mul_f32 v[26:27], v[74:75], v[26:27]
	v_pk_fma_f32 v[6:7], v[70:71], v[6:7], v[114:115]
	v_pk_fma_f32 v[4:5], v[80:81], v[4:5], v[112:113]
	v_pk_fma_f32 v[2:3], v[82:83], v[2:3], v[118:119]
	v_pk_fma_f32 v[0:1], v[84:85], v[0:1], v[116:117]
	v_pk_fma_f32 v[10:11], v[86:87], v[10:11], v[122:123]
	v_pk_fma_f32 v[8:9], v[88:89], v[8:9], v[120:121]
	v_pk_fma_f32 v[14:15], v[90:91], v[14:15], v[126:127]
	v_pk_fma_f32 v[12:13], v[92:93], v[12:13], v[124:125]
	v_pk_fma_f32 v[22:23], v[94:95], v[22:23], v[130:131]
	v_pk_fma_f32 v[20:21], v[96:97], v[20:21], v[128:129]
	v_pk_fma_f32 v[18:19], v[18:19], v[98:99], v[134:135]
	v_pk_fma_f32 v[16:17], v[16:17], v[100:101], v[132:133]
	v_pk_fma_f32 v[30:31], v[30:31], v[102:103], v[138:139]
	v_pk_fma_f32 v[28:29], v[28:29], v[104:105], v[136:137]
	v_pk_fma_f32 v[26:27], v[26:27], v[106:107], v[142:143]
	v_pk_fma_f32 v[24:25], v[24:25], v[108:109], v[140:141]
	v_bfe_u32 v60, v4, 16, 1
	v_bfe_u32 v64, v6, 16, 1
	v_bfe_u32 v66, v0, 16, 1
	v_bfe_u32 v67, v1, 16, 1
	v_bfe_u32 v68, v2, 16, 1
	v_bfe_u32 v61, v5, 16, 1
	v_bfe_u32 v65, v7, 16, 1
	v_bfe_u32 v69, v3, 16, 1
	v_bfe_u32 v70, v8, 16, 1
	v_bfe_u32 v71, v9, 16, 1
	v_bfe_u32 v72, v10, 16, 1
	v_bfe_u32 v73, v11, 16, 1
	v_bfe_u32 v74, v12, 16, 1
	v_bfe_u32 v75, v13, 16, 1
	v_bfe_u32 v76, v14, 16, 1
	v_bfe_u32 v77, v15, 16, 1
	v_bfe_u32 v78, v20, 16, 1
	v_bfe_u32 v79, v21, 16, 1
	v_bfe_u32 v80, v22, 16, 1
	v_bfe_u32 v81, v23, 16, 1
	v_bfe_u32 v82, v16, 16, 1
	v_bfe_u32 v84, v18, 16, 1
	v_bfe_u32 v86, v28, 16, 1
	v_bfe_u32 v87, v29, 16, 1
	v_bfe_u32 v88, v30, 16, 1
	v_bfe_u32 v89, v31, 16, 1
	v_bfe_u32 v90, v24, 16, 1
	v_bfe_u32 v92, v26, 16, 1
	v_add3_u32 v4, v4, v60, s16
	v_add3_u32 v6, v6, v64, s16
	v_add3_u32 v0, v0, v66, s16
	v_add3_u32 v60, v1, v67, s16
	v_add3_u32 v1, v2, v68, s16
	v_bfe_u32 v83, v17, 16, 1
	v_bfe_u32 v85, v19, 16, 1
	v_bfe_u32 v91, v25, 16, 1
	v_bfe_u32 v93, v27, 16, 1
	v_add3_u32 v5, v5, v61, s16
	v_add3_u32 v7, v7, v65, s16
	v_add3_u32 v3, v3, v69, s16
	v_add3_u32 v2, v8, v70, s16
	v_add3_u32 v8, v9, v71, s16
	v_add3_u32 v9, v10, v72, s16
	v_add3_u32 v10, v11, v73, s16
	v_add3_u32 v11, v12, v74, s16
	v_add3_u32 v12, v13, v75, s16
	v_add3_u32 v13, v14, v76, s16
	v_add3_u32 v14, v15, v77, s16
	v_add3_u32 v15, v20, v78, s16
	v_add3_u32 v20, v21, v79, s16
	v_add3_u32 v21, v22, v80, s16
	v_add3_u32 v22, v23, v81, s16
	v_add3_u32 v16, v16, v82, s16
	v_add3_u32 v18, v18, v84, s16
	v_add3_u32 v23, v28, v86, s16
	v_add3_u32 v28, v29, v87, s16
	v_add3_u32 v29, v30, v88, s16
	v_add3_u32 v30, v31, v89, s16
	v_add3_u32 v24, v24, v90, s16
	v_add3_u32 v26, v26, v92, s16
	v_lshrrev_b32_e32 v4, 16, v4
	v_lshrrev_b32_e32 v6, 16, v6
	v_lshrrev_b32_e32 v31, 16, v0
	v_lshrrev_b32_e32 v61, 16, v1
	v_add3_u32 v17, v17, v83, s16
	v_add3_u32 v19, v19, v85, s16
	v_add3_u32 v25, v25, v91, s16
	v_add3_u32 v27, v27, v93, s16
	v_lshrrev_b32_e32 v64, 16, v2
	v_lshrrev_b32_e32 v9, 16, v9
	v_lshrrev_b32_e32 v11, 16, v11
	v_lshrrev_b32_e32 v13, 16, v13
	v_lshrrev_b32_e32 v15, 16, v15
	v_lshrrev_b32_e32 v21, 16, v21
	v_lshrrev_b32_e32 v16, 16, v16
	v_lshrrev_b32_e32 v18, 16, v18
	v_lshrrev_b32_e32 v23, 16, v23
	v_lshrrev_b32_e32 v29, 16, v29
	v_lshrrev_b32_e32 v24, 16, v24
	v_lshrrev_b32_e32 v26, 16, v26
	v_and_or_b32 v0, v5, s10, v4
	v_and_or_b32 v1, v7, s10, v6
	v_and_or_b32 v2, v60, s10, v31
	v_and_or_b32 v3, v3, s10, v61
	v_and_or_b32 v4, v8, s10, v64
	v_and_or_b32 v5, v10, s10, v9
	v_and_or_b32 v6, v12, s10, v11
	v_and_or_b32 v7, v14, s10, v13
	v_and_or_b32 v8, v20, s10, v15
	v_and_or_b32 v9, v22, s10, v21
	v_and_or_b32 v10, v17, s10, v16
	v_and_or_b32 v11, v19, s10, v18
	v_and_or_b32 v12, v28, s10, v23
	v_and_or_b32 v13, v30, s10, v29
	v_and_or_b32 v14, v25, s10, v24
	v_and_or_b32 v15, v27, s10, v26
	flat_store_dwordx4 v[58:59], v[0:3]
	flat_store_dwordx4 v[58:59], v[4:7] offset:1024
	flat_store_dwordx4 v[58:59], v[8:11] offset:2048
	flat_store_dwordx4 v[58:59], v[12:15] offset:3072
	s_cmpk_lt_i32 s18, 0x4000
	s_cbranch_scc1 .LBB0_1946
